# scan: consumer runs 32 steps straight, mid-chunk workgroup barrier replaced by producer-only LDS counter sync; no grid barrier between phase 0 and 1
# speedup vs baseline: 1.0120x; 1.0120x over previous
.LBB0_804:
	s_or_b64 exec, exec, s[52:53]
	v_lshlrev_b32_e32 v0, 3, v54
	v_lshrrev_b32_e32 v8, 3, v57
	v_and_or_b32 v0, v0, 24, v8
	v_mov_b32_e32 v8, 2
	v_lshlrev_b32_sdwa v8, v8, v166 dst_sel:DWORD dst_unused:UNUSED_PAD src0_sel:DWORD src1_sel:BYTE_0
	v_and_b32_e32 v9, 28, v8
	s_and_b32 s4, s4, 0x3e0
	v_readlane_b32 s8, v253, 21
	v_or_b32_e32 v8, s4, v9
	s_movk_i32 s4, 0x90
	v_mov_b32_e32 v42, s8
	v_readlane_b32 s9, v253, 22
	v_lshrrev_b32_sdwa v100, v231, v166 dst_sel:DWORD dst_unused:UNUSED_PAD src0_sel:DWORD src1_sel:BYTE_0
	v_mad_u32_u24 v44, v59, s4, v42
	v_mov_b32_e32 v42, s9
	v_mul_u32_u24_e32 v102, 36, v0
	v_lshlrev_b32_e32 v41, 7, v100
	v_lshlrev_b32_e32 v103, 2, v9
	v_readlane_b32 s20, v253, 24
	v_mad_u32_u24 v45, v59, s4, v42
	v_mov_b32_e32 v42, 0x900
	v_lshlrev_b32_e32 v0, 2, v0
	v_lshlrev_b32_e32 v108, 3, v40
	v_lshlrev_b32_e32 v40, 7, v51
	v_add3_u32 v105, s20, v41, v103
	v_mad_u32_u24 v42, v59, s4, v42
	v_add3_u32 v111, s20, v0, v40
	v_add3_u32 v113, 0, v41, v103
	v_lshlrev_b64 v[40:41], 11, v[46:47]
	v_lshlrev_b32_e32 v46, 1, v48
	v_add_lshl_u32 v0, s5, v48, 1
	v_add_u32_e32 v57, s8, v42
	v_add_u32_e32 v117, s9, v42
	v_or_b32_e32 v42, v40, v46
	v_mov_b32_e32 v43, v41
	v_lshl_add_u64 v[40:41], v[40:41], 0, v[0:1]
	v_lshl_add_u64 v[40:41], s[14:15], 0, v[40:41]
	s_mov_b64 s[4:5], 0x3e28000
	s_movk_i32 s8, 0x180
	v_lshl_add_u64 v[82:83], v[40:41], 0, s[4:5]
	v_mad_u64_u32 v[40:41], s[4:5], v36, s8, 0
	v_mov_b32_e32 v36, v41
	v_mad_u64_u32 v[36:37], s[4:5], v37, s8, v[36:37]
	v_mov_b32_e32 v41, v36
	v_mov_b32_e32 v36, 0x180000
	v_mad_i64_i32 v[36:37], s[4:5], s18, v36, v[40:41]
	v_lshl_add_u64 v[34:35], v[34:35], 1, v[36:37]
	v_lshl_add_u64 v[34:35], s[94:95], 0, v[34:35]
	s_mov_b64 s[4:5], 0x6080
	v_lshl_add_u64 v[84:85], v[34:35], 0, s[4:5]
	s_lshl_b64 s[4:5], s[18:19], 23
	v_lshlrev_b64 v[34:35], 11, v[60:61]
	v_lshl_add_u64 v[34:35], s[4:5], 0, v[34:35]
	v_or_b32_e32 v36, v34, v46
	v_mov_b32_e32 v37, v35
	v_lshl_add_u64 v[34:35], v[34:35], 0, v[0:1]
	v_and_b32_e32 v106, 28, v50
	v_lshl_add_u64 v[86:87], s[14:15], 0, v[36:37]
	v_lshl_add_u64 v[34:35], s[14:15], 0, v[34:35]
	s_mov_b64 s[4:5], 0x3e20000
	v_mov_b32_e32 v36, v1
	v_mov_b32_e32 v37, v1
	v_mul_u32_u24_e32 v54, 0x50, v59
	v_mul_u32_u24_e32 v50, 36, v106
	v_lshl_add_u64 v[88:89], v[34:35], 0, s[4:5]
	v_mov_b32_e32 v34, v1
	v_mov_b32_e32 v35, v1
	v_lshlrev_b32_e32 v120, 2, v38
	v_lshlrev_b32_e32 v121, 2, v39
	v_mov_b64_e32 v[40:41], v[36:37]
	v_lshlrev_b32_e32 v101, 2, v51
	v_cmp_eq_u32_e64 s[48:49], 0, v51
	s_mov_b32 s30, 1
	v_cmp_eq_u32_e64 s[50:51], 1, v51
	v_cmp_eq_u32_e64 s[52:53], 2, v51
	v_cmp_eq_u32_e64 s[54:55], 3, v51
	v_cmp_eq_u32_e64 s[56:57], 4, v51
	v_cmp_eq_u32_e64 s[58:59], 5, v51
	v_cmp_eq_u32_e64 s[60:61], 6, v51
	v_cmp_eq_u32_e64 s[62:63], 7, v51
	v_lshlrev_b32_e32 v104, 5, v100
	v_cmp_eq_u32_e64 s[24:25], 0, v49
	v_lshlrev_b32_e32 v107, 3, v60
	v_lshlrev_b32_e32 v109, 12, v53
	v_lshlrev_b32_e32 v110, 10, v52
	v_sub_u32_e32 v112, 0, v58
	v_mul_u32_u24_e32 v114, 0x8c, v106
	v_lshl_add_u64 v[80:81], s[14:15], 0, v[42:43]
	v_or_b32_e32 v0, 0xffffffe0, v100
	s_mov_b64 s[20:21], 0
	v_add_u32_e32 v61, v44, v55
	v_add_u32_e32 v115, v45, v55
	v_add_u32_e32 v116, v57, v55
	v_add_u32_e32 v117, v117, v55
	v_lshlrev_b32_e32 v118, 2, v50
	v_add_u32_e32 v119, v56, v54
	v_mov_b64_e32 v[38:39], v[34:35]
	s_mov_b32 s100, 0
	v_mov_b32_e32 v42, 0x21f00
	v_mov_b32_e32 v43, 0
	ds_write_b32 v42, v43
	s_waitcnt vmcnt(0) lgkmcnt(0)
	s_barrier
	s_branch .LBB0_808

.LBB0_808:
	s_add_i32 s31, s30, -1
	s_and_b32 s8, s31, 1
	s_mul_i32 s4, s8, 0xc300
	s_add_i32 s5, s4, 0
	s_bitcmp1_b32 s30, 0
	s_cselect_b32 s4, 0xc300, 0
	v_lshl_add_u32 v124, v101, 2, s5
	v_lshl_add_u32 v123, v102, 2, s5
	v_lshl_add_u32 v122, s8, 12, v111
	s_and_saveexec_b64 s[8:9], s[42:43]
	s_xor_b64 s[18:19], exec, s[8:9]
	s_cbranch_execz .LBB0_810
	s_setprio 3
	v_and_b32_e32 v213, 15, v166
	v_lshlrev_b32_e32 v208, 4, v213
	v_add_u32_e32 v208, s5, v208
	ds_read_b128 v[128:131], v208 offset:0
	ds_read_b128 v[132:135], v208 offset:256
	v_lshrrev_b32_e32 v214, 4, v166
	v_and_b32_e32 v215, 1, v166
	v_lshl_or_b32 v214, v214, 1, v215
	ds_read_b128 v[136:139], v208 offset:16384
	ds_read_b128 v[140:143], v208 offset:24576
	ds_read_b128 v[144:147], v208 offset:32768
	v_mul_u32_u24_e32 v209, 0x90, v214
	v_xor_b32_e32 v216, 1, v214
	v_add_u32_e32 v209, s5, v209
	v_mul_u32_u24_e32 v210, 0x90, v216
	v_mov_b32_e32 v211, s5
	v_add_u32_e32 v210, s5, v210
	ds_read_b128 v[176:179], v209 offset:40960
	ds_read_b128 v[180:183], v210 offset:40960
	ds_read_b128 v[184:187], v211 offset:49664
	ds_read_b128 v[188:191], v211 offset:49680
	ds_read_b128 v[148:151], v208 offset:512
	ds_read_b128 v[152:155], v208 offset:768
	ds_read_b128 v[156:159], v208 offset:16640
	ds_read_b128 v[168:171], v208 offset:24832
	ds_read_b128 v[172:175], v208 offset:33024
	v_lshrrev_b32_e32 v217, 1, v213
	v_lshlrev_b32_e32 v212, 7, v217
	v_lshl_add_u32 v212, v214, 2, v212
	v_lshrrev_b32_e32 v218, 2, v211
	v_and_b32_e32 v218, 0x1000, v218
	v_add_u32_e32 v212, v212, v218
	v_add_u32_e32 v212, 0x18600, v212
	v_cmp_eq_u32_e64 s[48:49], 0, v217
	v_cmp_eq_u32_e64 s[50:51], 1, v217
	v_cmp_eq_u32_e64 s[52:53], 2, v217
	v_cmp_eq_u32_e64 s[54:55], 3, v217
	v_cmp_eq_u32_e64 s[56:57], 4, v217
	v_cmp_eq_u32_e64 s[58:59], 5, v217
	v_cmp_eq_u32_e64 s[60:61], 6, v217
	v_cmp_eq_u32_e64 s[62:63], 7, v217
	s_waitcnt lgkmcnt(5)
	v_pk_mul_f32 v[42:43], v[34:35], v[128:129] op_sel_hi:[0,1]
	v_pk_mul_f32 v[44:45], v[38:39], v[128:129] op_sel_hi:[0,1]
	v_pk_fma_f32 v[42:43], v[34:35], v[130:131], v[42:43] op_sel:[1,0,0]
	v_pk_fma_f32 v[44:45], v[38:39], v[130:131], v[44:45] op_sel:[1,0,0]
	v_pk_fma_f32 v[42:43], v[36:37], v[132:133], v[42:43] op_sel_hi:[0,1,1]
	v_pk_fma_f32 v[44:45], v[40:41], v[132:133], v[44:45] op_sel_hi:[0,1,1]
	v_pk_fma_f32 v[42:43], v[36:37], v[134:135], v[42:43] op_sel:[1,0,0]
	v_pk_fma_f32 v[44:45], v[40:41], v[134:135], v[44:45] op_sel:[1,0,0]
	v_pk_mul_f32 v[46:47], v[144:145], v[176:177] op_sel_hi:[1,0]
	v_pk_mul_f32 v[48:49], v[146:147], v[176:177] op_sel_hi:[1,0]
	v_add_f32_dpp v42, v44, v42 quad_perm:[1,0,3,2] row_mask:0xf bank_mask:0xf bound_ctrl:1
	v_add_f32_dpp v43, v45, v43 quad_perm:[1,0,3,2] row_mask:0xf bank_mask:0xf bound_ctrl:1
	v_pk_mul_f32 v[50:51], v[144:145], v[180:181] op_sel_hi:[1,0]
	v_add_f32_dpp v42, v42, v42 quad_perm:[2,3,0,1] row_mask:0xf bank_mask:0xf bound_ctrl:1
	v_add_f32_dpp v43, v43, v43 quad_perm:[2,3,0,1] row_mask:0xf bank_mask:0xf bound_ctrl:1
	v_pk_mul_f32 v[52:53], v[146:147], v[180:181] op_sel_hi:[1,0]
	v_add_f32_dpp v42, v42, v42 row_ror:4 row_mask:0xf bank_mask:0xf bound_ctrl:1
	v_add_f32_dpp v43, v43, v43 row_ror:4 row_mask:0xf bank_mask:0xf bound_ctrl:1
	ds_read_b128 v[128:131], v208 offset:1024
	v_add_f32_dpp v42, v42, v42 row_ror:8 row_mask:0xf bank_mask:0xf bound_ctrl:1
	v_add_f32_dpp v43, v43, v43 row_ror:8 row_mask:0xf bank_mask:0xf bound_ctrl:1
	v_pk_fma_f32 v[46:47], v[140:141], v[42:43], v[46:47] op_sel_hi:[1,0,1]
	v_mov_b32_dpp v54, v42 quad_perm:[1,0,3,2] row_mask:0xf bank_mask:0xf bound_ctrl:1
	v_pk_fma_f32 v[48:49], v[142:143], v[42:43], v[48:49] op_sel_hi:[1,0,1]
	v_fmac_f32_e32 v43, v184, v42
	v_pk_fma_f32 v[34:35], v[34:35], v[136:137], v[46:47]
	v_pk_fma_f32 v[36:37], v[36:37], v[138:139], v[48:49]
	v_pk_fma_f32 v[50:51], v[140:141], v[54:55], v[50:51] op_sel_hi:[1,0,1]
	v_pk_fma_f32 v[52:53], v[142:143], v[54:55], v[52:53] op_sel_hi:[1,0,1]
	v_fmac_f32_e32 v43, v176, v185
	v_pk_fma_f32 v[38:39], v[38:39], v[136:137], v[50:51]
	v_pk_fma_f32 v[40:41], v[40:41], v[138:139], v[52:53]
	v_cndmask_b32_e64 v55, 0, v43, s[48:49]
	ds_read_b128 v[132:135], v208 offset:1280
	ds_read_b128 v[136:139], v208 offset:16896
	ds_read_b128 v[140:143], v208 offset:25088
	ds_read_b128 v[144:147], v208 offset:33280
	s_waitcnt lgkmcnt(5)
	v_pk_mul_f32 v[42:43], v[34:35], v[148:149] op_sel_hi:[0,1]
	v_pk_mul_f32 v[44:45], v[38:39], v[148:149] op_sel_hi:[0,1]
	v_pk_fma_f32 v[42:43], v[34:35], v[150:151], v[42:43] op_sel:[1,0,0]
	v_pk_fma_f32 v[44:45], v[38:39], v[150:151], v[44:45] op_sel:[1,0,0]
	v_pk_fma_f32 v[42:43], v[36:37], v[152:153], v[42:43] op_sel_hi:[0,1,1]
	v_pk_fma_f32 v[44:45], v[40:41], v[152:153], v[44:45] op_sel_hi:[0,1,1]
	v_pk_fma_f32 v[42:43], v[36:37], v[154:155], v[42:43] op_sel:[1,0,0]
	v_pk_fma_f32 v[44:45], v[40:41], v[154:155], v[44:45] op_sel:[1,0,0]
	v_pk_mul_f32 v[46:47], v[172:173], v[176:177] op_sel:[0,1]
	v_pk_mul_f32 v[48:49], v[174:175], v[176:177] op_sel:[0,1]
	v_add_f32_dpp v42, v44, v42 quad_perm:[1,0,3,2] row_mask:0xf bank_mask:0xf bound_ctrl:1
	v_add_f32_dpp v43, v45, v43 quad_perm:[1,0,3,2] row_mask:0xf bank_mask:0xf bound_ctrl:1
	v_pk_mul_f32 v[50:51], v[172:173], v[180:181] op_sel:[0,1]
	v_add_f32_dpp v42, v42, v42 quad_perm:[2,3,0,1] row_mask:0xf bank_mask:0xf bound_ctrl:1
	v_add_f32_dpp v43, v43, v43 quad_perm:[2,3,0,1] row_mask:0xf bank_mask:0xf bound_ctrl:1
	v_pk_mul_f32 v[52:53], v[174:175], v[180:181] op_sel:[0,1]
	v_add_f32_dpp v42, v42, v42 row_ror:4 row_mask:0xf bank_mask:0xf bound_ctrl:1
	v_add_f32_dpp v43, v43, v43 row_ror:4 row_mask:0xf bank_mask:0xf bound_ctrl:1
	ds_read_b128 v[148:151], v208 offset:1536
	v_add_f32_dpp v42, v42, v42 row_ror:8 row_mask:0xf bank_mask:0xf bound_ctrl:1
	v_add_f32_dpp v43, v43, v43 row_ror:8 row_mask:0xf bank_mask:0xf bound_ctrl:1
	v_pk_fma_f32 v[46:47], v[168:169], v[42:43], v[46:47] op_sel_hi:[1,0,1]
	v_mov_b32_dpp v54, v42 quad_perm:[1,0,3,2] row_mask:0xf bank_mask:0xf bound_ctrl:1
	v_pk_fma_f32 v[48:49], v[170:171], v[42:43], v[48:49] op_sel_hi:[1,0,1]
	v_fmac_f32_e32 v43, v186, v42
	v_pk_fma_f32 v[34:35], v[34:35], v[156:157], v[46:47]
	v_pk_fma_f32 v[36:37], v[36:37], v[158:159], v[48:49]
	v_pk_fma_f32 v[50:51], v[168:169], v[54:55], v[50:51] op_sel_hi:[1,0,1]
	v_pk_fma_f32 v[52:53], v[170:171], v[54:55], v[52:53] op_sel_hi:[1,0,1]
	v_fmac_f32_e32 v43, v177, v187
	v_pk_fma_f32 v[38:39], v[38:39], v[156:157], v[50:51]
	v_pk_fma_f32 v[40:41], v[40:41], v[158:159], v[52:53]
	v_cndmask_b32_e64 v55, v55, v43, s[50:51]
	ds_read_b128 v[152:155], v208 offset:1792
	ds_read_b128 v[156:159], v208 offset:17152
	ds_read_b128 v[168:171], v208 offset:25344
	ds_read_b128 v[172:175], v208 offset:33536
	ds_read_b128 v[192:195], v209 offset:40976
	ds_read_b128 v[196:199], v210 offset:40976
	ds_read_b128 v[200:203], v211 offset:49696
	ds_read_b128 v[204:207], v211 offset:49712
	s_waitcnt lgkmcnt(9)
	v_pk_mul_f32 v[42:43], v[34:35], v[128:129] op_sel_hi:[0,1]
	v_pk_mul_f32 v[44:45], v[38:39], v[128:129] op_sel_hi:[0,1]
	v_pk_fma_f32 v[42:43], v[34:35], v[130:131], v[42:43] op_sel:[1,0,0]
	v_pk_fma_f32 v[44:45], v[38:39], v[130:131], v[44:45] op_sel:[1,0,0]
	v_pk_fma_f32 v[42:43], v[36:37], v[132:133], v[42:43] op_sel_hi:[0,1,1]
	v_pk_fma_f32 v[44:45], v[40:41], v[132:133], v[44:45] op_sel_hi:[0,1,1]
	v_pk_fma_f32 v[42:43], v[36:37], v[134:135], v[42:43] op_sel:[1,0,0]
	v_pk_fma_f32 v[44:45], v[40:41], v[134:135], v[44:45] op_sel:[1,0,0]
	v_pk_mul_f32 v[46:47], v[144:145], v[178:179] op_sel_hi:[1,0]
	v_pk_mul_f32 v[48:49], v[146:147], v[178:179] op_sel_hi:[1,0]
	v_add_f32_dpp v42, v44, v42 quad_perm:[1,0,3,2] row_mask:0xf bank_mask:0xf bound_ctrl:1
	v_add_f32_dpp v43, v45, v43 quad_perm:[1,0,3,2] row_mask:0xf bank_mask:0xf bound_ctrl:1
	v_pk_mul_f32 v[50:51], v[144:145], v[182:183] op_sel_hi:[1,0]
	v_add_f32_dpp v42, v42, v42 quad_perm:[2,3,0,1] row_mask:0xf bank_mask:0xf bound_ctrl:1
	v_add_f32_dpp v43, v43, v43 quad_perm:[2,3,0,1] row_mask:0xf bank_mask:0xf bound_ctrl:1
	v_pk_mul_f32 v[52:53], v[146:147], v[182:183] op_sel_hi:[1,0]
	v_add_f32_dpp v42, v42, v42 row_ror:4 row_mask:0xf bank_mask:0xf bound_ctrl:1
	v_add_f32_dpp v43, v43, v43 row_ror:4 row_mask:0xf bank_mask:0xf bound_ctrl:1
	ds_read_b128 v[128:131], v208 offset:2048
	v_add_f32_dpp v42, v42, v42 row_ror:8 row_mask:0xf bank_mask:0xf bound_ctrl:1
	v_add_f32_dpp v43, v43, v43 row_ror:8 row_mask:0xf bank_mask:0xf bound_ctrl:1
	v_pk_fma_f32 v[46:47], v[140:141], v[42:43], v[46:47] op_sel_hi:[1,0,1]
	v_mov_b32_dpp v54, v42 quad_perm:[1,0,3,2] row_mask:0xf bank_mask:0xf bound_ctrl:1
	v_pk_fma_f32 v[48:49], v[142:143], v[42:43], v[48:49] op_sel_hi:[1,0,1]
	v_fmac_f32_e32 v43, v188, v42
	v_pk_fma_f32 v[34:35], v[34:35], v[136:137], v[46:47]
	v_pk_fma_f32 v[36:37], v[36:37], v[138:139], v[48:49]
	v_pk_fma_f32 v[50:51], v[140:141], v[54:55], v[50:51] op_sel_hi:[1,0,1]
	v_pk_fma_f32 v[52:53], v[142:143], v[54:55], v[52:53] op_sel_hi:[1,0,1]
	v_fmac_f32_e32 v43, v178, v189
	v_pk_fma_f32 v[38:39], v[38:39], v[136:137], v[50:51]
	v_pk_fma_f32 v[40:41], v[40:41], v[138:139], v[52:53]
	v_cndmask_b32_e64 v55, v55, v43, s[52:53]
	ds_read_b128 v[132:135], v208 offset:2304
	ds_read_b128 v[136:139], v208 offset:17408
	ds_read_b128 v[140:143], v208 offset:25600
	ds_read_b128 v[144:147], v208 offset:33792
	s_waitcnt lgkmcnt(9)
	v_pk_mul_f32 v[42:43], v[34:35], v[148:149] op_sel_hi:[0,1]
	v_pk_mul_f32 v[44:45], v[38:39], v[148:149] op_sel_hi:[0,1]
	v_pk_fma_f32 v[42:43], v[34:35], v[150:151], v[42:43] op_sel:[1,0,0]
	v_pk_fma_f32 v[44:45], v[38:39], v[150:151], v[44:45] op_sel:[1,0,0]
	v_pk_fma_f32 v[42:43], v[36:37], v[152:153], v[42:43] op_sel_hi:[0,1,1]
	v_pk_fma_f32 v[44:45], v[40:41], v[152:153], v[44:45] op_sel_hi:[0,1,1]
	v_pk_fma_f32 v[42:43], v[36:37], v[154:155], v[42:43] op_sel:[1,0,0]
	v_pk_fma_f32 v[44:45], v[40:41], v[154:155], v[44:45] op_sel:[1,0,0]
	v_pk_mul_f32 v[46:47], v[172:173], v[178:179] op_sel:[0,1]
	v_pk_mul_f32 v[48:49], v[174:175], v[178:179] op_sel:[0,1]
	v_add_f32_dpp v42, v44, v42 quad_perm:[1,0,3,2] row_mask:0xf bank_mask:0xf bound_ctrl:1
	v_add_f32_dpp v43, v45, v43 quad_perm:[1,0,3,2] row_mask:0xf bank_mask:0xf bound_ctrl:1
	v_pk_mul_f32 v[50:51], v[172:173], v[182:183] op_sel:[0,1]
	v_add_f32_dpp v42, v42, v42 quad_perm:[2,3,0,1] row_mask:0xf bank_mask:0xf bound_ctrl:1
	v_add_f32_dpp v43, v43, v43 quad_perm:[2,3,0,1] row_mask:0xf bank_mask:0xf bound_ctrl:1
	v_pk_mul_f32 v[52:53], v[174:175], v[182:183] op_sel:[0,1]
	v_add_f32_dpp v42, v42, v42 row_ror:4 row_mask:0xf bank_mask:0xf bound_ctrl:1
	v_add_f32_dpp v43, v43, v43 row_ror:4 row_mask:0xf bank_mask:0xf bound_ctrl:1
	ds_read_b128 v[148:151], v208 offset:2560
	v_add_f32_dpp v42, v42, v42 row_ror:8 row_mask:0xf bank_mask:0xf bound_ctrl:1
	v_add_f32_dpp v43, v43, v43 row_ror:8 row_mask:0xf bank_mask:0xf bound_ctrl:1
	v_pk_fma_f32 v[46:47], v[168:169], v[42:43], v[46:47] op_sel_hi:[1,0,1]
	v_mov_b32_dpp v54, v42 quad_perm:[1,0,3,2] row_mask:0xf bank_mask:0xf bound_ctrl:1
	v_pk_fma_f32 v[48:49], v[170:171], v[42:43], v[48:49] op_sel_hi:[1,0,1]
	v_fmac_f32_e32 v43, v190, v42
	v_pk_fma_f32 v[34:35], v[34:35], v[156:157], v[46:47]
	v_pk_fma_f32 v[36:37], v[36:37], v[158:159], v[48:49]
	v_pk_fma_f32 v[50:51], v[168:169], v[54:55], v[50:51] op_sel_hi:[1,0,1]
	v_pk_fma_f32 v[52:53], v[170:171], v[54:55], v[52:53] op_sel_hi:[1,0,1]
	v_fmac_f32_e32 v43, v179, v191
	v_pk_fma_f32 v[38:39], v[38:39], v[156:157], v[50:51]
	v_pk_fma_f32 v[40:41], v[40:41], v[158:159], v[52:53]
	v_cndmask_b32_e64 v55, v55, v43, s[54:55]
	ds_read_b128 v[152:155], v208 offset:2816
	ds_read_b128 v[156:159], v208 offset:17664
	ds_read_b128 v[168:171], v208 offset:25856
	ds_read_b128 v[172:175], v208 offset:34048
	s_waitcnt lgkmcnt(5)
	v_pk_mul_f32 v[42:43], v[34:35], v[128:129] op_sel_hi:[0,1]
	v_pk_mul_f32 v[44:45], v[38:39], v[128:129] op_sel_hi:[0,1]
	v_pk_fma_f32 v[42:43], v[34:35], v[130:131], v[42:43] op_sel:[1,0,0]
	v_pk_fma_f32 v[44:45], v[38:39], v[130:131], v[44:45] op_sel:[1,0,0]
	v_pk_fma_f32 v[42:43], v[36:37], v[132:133], v[42:43] op_sel_hi:[0,1,1]
	v_pk_fma_f32 v[44:45], v[40:41], v[132:133], v[44:45] op_sel_hi:[0,1,1]
	v_pk_fma_f32 v[42:43], v[36:37], v[134:135], v[42:43] op_sel:[1,0,0]
	v_pk_fma_f32 v[44:45], v[40:41], v[134:135], v[44:45] op_sel:[1,0,0]
	v_pk_mul_f32 v[46:47], v[144:145], v[192:193] op_sel_hi:[1,0]
	v_pk_mul_f32 v[48:49], v[146:147], v[192:193] op_sel_hi:[1,0]
	v_add_f32_dpp v42, v44, v42 quad_perm:[1,0,3,2] row_mask:0xf bank_mask:0xf bound_ctrl:1
	v_add_f32_dpp v43, v45, v43 quad_perm:[1,0,3,2] row_mask:0xf bank_mask:0xf bound_ctrl:1
	v_pk_mul_f32 v[50:51], v[144:145], v[196:197] op_sel_hi:[1,0]
	v_add_f32_dpp v42, v42, v42 quad_perm:[2,3,0,1] row_mask:0xf bank_mask:0xf bound_ctrl:1
	v_add_f32_dpp v43, v43, v43 quad_perm:[2,3,0,1] row_mask:0xf bank_mask:0xf bound_ctrl:1
	v_pk_mul_f32 v[52:53], v[146:147], v[196:197] op_sel_hi:[1,0]
	v_add_f32_dpp v42, v42, v42 row_ror:4 row_mask:0xf bank_mask:0xf bound_ctrl:1
	v_add_f32_dpp v43, v43, v43 row_ror:4 row_mask:0xf bank_mask:0xf bound_ctrl:1
	ds_read_b128 v[128:131], v208 offset:3072
	v_add_f32_dpp v42, v42, v42 row_ror:8 row_mask:0xf bank_mask:0xf bound_ctrl:1
	v_add_f32_dpp v43, v43, v43 row_ror:8 row_mask:0xf bank_mask:0xf bound_ctrl:1
	v_pk_fma_f32 v[46:47], v[140:141], v[42:43], v[46:47] op_sel_hi:[1,0,1]
	v_mov_b32_dpp v54, v42 quad_perm:[1,0,3,2] row_mask:0xf bank_mask:0xf bound_ctrl:1
	v_pk_fma_f32 v[48:49], v[142:143], v[42:43], v[48:49] op_sel_hi:[1,0,1]
	v_fmac_f32_e32 v43, v200, v42
	v_pk_fma_f32 v[34:35], v[34:35], v[136:137], v[46:47]
	v_pk_fma_f32 v[36:37], v[36:37], v[138:139], v[48:49]
	v_pk_fma_f32 v[50:51], v[140:141], v[54:55], v[50:51] op_sel_hi:[1,0,1]
	v_pk_fma_f32 v[52:53], v[142:143], v[54:55], v[52:53] op_sel_hi:[1,0,1]
	v_fmac_f32_e32 v43, v192, v201
	v_pk_fma_f32 v[38:39], v[38:39], v[136:137], v[50:51]
	v_pk_fma_f32 v[40:41], v[40:41], v[138:139], v[52:53]
	v_cndmask_b32_e64 v55, v55, v43, s[56:57]
	ds_read_b128 v[132:135], v208 offset:3328
	ds_read_b128 v[136:139], v208 offset:17920
	ds_read_b128 v[140:143], v208 offset:26112
	ds_read_b128 v[144:147], v208 offset:34304
	s_waitcnt lgkmcnt(5)
	v_pk_mul_f32 v[42:43], v[34:35], v[148:149] op_sel_hi:[0,1]
	v_pk_mul_f32 v[44:45], v[38:39], v[148:149] op_sel_hi:[0,1]
	v_pk_fma_f32 v[42:43], v[34:35], v[150:151], v[42:43] op_sel:[1,0,0]
	v_pk_fma_f32 v[44:45], v[38:39], v[150:151], v[44:45] op_sel:[1,0,0]
	v_pk_fma_f32 v[42:43], v[36:37], v[152:153], v[42:43] op_sel_hi:[0,1,1]
	v_pk_fma_f32 v[44:45], v[40:41], v[152:153], v[44:45] op_sel_hi:[0,1,1]
	v_pk_fma_f32 v[42:43], v[36:37], v[154:155], v[42:43] op_sel:[1,0,0]
	v_pk_fma_f32 v[44:45], v[40:41], v[154:155], v[44:45] op_sel:[1,0,0]
	v_pk_mul_f32 v[46:47], v[172:173], v[192:193] op_sel:[0,1]
	v_pk_mul_f32 v[48:49], v[174:175], v[192:193] op_sel:[0,1]
	v_add_f32_dpp v42, v44, v42 quad_perm:[1,0,3,2] row_mask:0xf bank_mask:0xf bound_ctrl:1
	v_add_f32_dpp v43, v45, v43 quad_perm:[1,0,3,2] row_mask:0xf bank_mask:0xf bound_ctrl:1
	v_pk_mul_f32 v[50:51], v[172:173], v[196:197] op_sel:[0,1]
	v_add_f32_dpp v42, v42, v42 quad_perm:[2,3,0,1] row_mask:0xf bank_mask:0xf bound_ctrl:1
	v_add_f32_dpp v43, v43, v43 quad_perm:[2,3,0,1] row_mask:0xf bank_mask:0xf bound_ctrl:1
	v_pk_mul_f32 v[52:53], v[174:175], v[196:197] op_sel:[0,1]
	v_add_f32_dpp v42, v42, v42 row_ror:4 row_mask:0xf bank_mask:0xf bound_ctrl:1
	v_add_f32_dpp v43, v43, v43 row_ror:4 row_mask:0xf bank_mask:0xf bound_ctrl:1
	ds_read_b128 v[148:151], v208 offset:3584
	v_add_f32_dpp v42, v42, v42 row_ror:8 row_mask:0xf bank_mask:0xf bound_ctrl:1
	v_add_f32_dpp v43, v43, v43 row_ror:8 row_mask:0xf bank_mask:0xf bound_ctrl:1
	v_pk_fma_f32 v[46:47], v[168:169], v[42:43], v[46:47] op_sel_hi:[1,0,1]
	v_mov_b32_dpp v54, v42 quad_perm:[1,0,3,2] row_mask:0xf bank_mask:0xf bound_ctrl:1
	v_pk_fma_f32 v[48:49], v[170:171], v[42:43], v[48:49] op_sel_hi:[1,0,1]
	v_fmac_f32_e32 v43, v202, v42
	v_pk_fma_f32 v[34:35], v[34:35], v[156:157], v[46:47]
	v_pk_fma_f32 v[36:37], v[36:37], v[158:159], v[48:49]
	v_pk_fma_f32 v[50:51], v[168:169], v[54:55], v[50:51] op_sel_hi:[1,0,1]
	v_pk_fma_f32 v[52:53], v[170:171], v[54:55], v[52:53] op_sel_hi:[1,0,1]
	v_fmac_f32_e32 v43, v193, v203
	v_pk_fma_f32 v[38:39], v[38:39], v[156:157], v[50:51]
	v_pk_fma_f32 v[40:41], v[40:41], v[158:159], v[52:53]
	v_cndmask_b32_e64 v55, v55, v43, s[58:59]
	ds_read_b128 v[152:155], v208 offset:3840
	ds_read_b128 v[156:159], v208 offset:18176
	ds_read_b128 v[168:171], v208 offset:26368
	ds_read_b128 v[172:175], v208 offset:34560
	ds_read_b128 v[176:179], v209 offset:40992
	ds_read_b128 v[180:183], v210 offset:40992
	ds_read_b128 v[184:187], v211 offset:49728
	ds_read_b128 v[188:191], v211 offset:49744
	s_waitcnt lgkmcnt(9)
	v_pk_mul_f32 v[42:43], v[34:35], v[128:129] op_sel_hi:[0,1]
	v_pk_mul_f32 v[44:45], v[38:39], v[128:129] op_sel_hi:[0,1]
	v_pk_fma_f32 v[42:43], v[34:35], v[130:131], v[42:43] op_sel:[1,0,0]
	v_pk_fma_f32 v[44:45], v[38:39], v[130:131], v[44:45] op_sel:[1,0,0]
	v_pk_fma_f32 v[42:43], v[36:37], v[132:133], v[42:43] op_sel_hi:[0,1,1]
	v_pk_fma_f32 v[44:45], v[40:41], v[132:133], v[44:45] op_sel_hi:[0,1,1]
	v_pk_fma_f32 v[42:43], v[36:37], v[134:135], v[42:43] op_sel:[1,0,0]
	v_pk_fma_f32 v[44:45], v[40:41], v[134:135], v[44:45] op_sel:[1,0,0]
	v_pk_mul_f32 v[46:47], v[144:145], v[194:195] op_sel_hi:[1,0]
	v_pk_mul_f32 v[48:49], v[146:147], v[194:195] op_sel_hi:[1,0]
	v_add_f32_dpp v42, v44, v42 quad_perm:[1,0,3,2] row_mask:0xf bank_mask:0xf bound_ctrl:1
	v_add_f32_dpp v43, v45, v43 quad_perm:[1,0,3,2] row_mask:0xf bank_mask:0xf bound_ctrl:1
	v_pk_mul_f32 v[50:51], v[144:145], v[198:199] op_sel_hi:[1,0]
	v_add_f32_dpp v42, v42, v42 quad_perm:[2,3,0,1] row_mask:0xf bank_mask:0xf bound_ctrl:1
	v_add_f32_dpp v43, v43, v43 quad_perm:[2,3,0,1] row_mask:0xf bank_mask:0xf bound_ctrl:1
	v_pk_mul_f32 v[52:53], v[146:147], v[198:199] op_sel_hi:[1,0]
	v_add_f32_dpp v42, v42, v42 row_ror:4 row_mask:0xf bank_mask:0xf bound_ctrl:1
	v_add_f32_dpp v43, v43, v43 row_ror:4 row_mask:0xf bank_mask:0xf bound_ctrl:1
	ds_read_b128 v[128:131], v208 offset:4096
	v_add_f32_dpp v42, v42, v42 row_ror:8 row_mask:0xf bank_mask:0xf bound_ctrl:1
	v_add_f32_dpp v43, v43, v43 row_ror:8 row_mask:0xf bank_mask:0xf bound_ctrl:1
	v_pk_fma_f32 v[46:47], v[140:141], v[42:43], v[46:47] op_sel_hi:[1,0,1]
	v_mov_b32_dpp v54, v42 quad_perm:[1,0,3,2] row_mask:0xf bank_mask:0xf bound_ctrl:1
	v_pk_fma_f32 v[48:49], v[142:143], v[42:43], v[48:49] op_sel_hi:[1,0,1]
	v_fmac_f32_e32 v43, v204, v42
	v_pk_fma_f32 v[34:35], v[34:35], v[136:137], v[46:47]
	v_pk_fma_f32 v[36:37], v[36:37], v[138:139], v[48:49]
	v_pk_fma_f32 v[50:51], v[140:141], v[54:55], v[50:51] op_sel_hi:[1,0,1]
	v_pk_fma_f32 v[52:53], v[142:143], v[54:55], v[52:53] op_sel_hi:[1,0,1]
	v_fmac_f32_e32 v43, v194, v205
	v_pk_fma_f32 v[38:39], v[38:39], v[136:137], v[50:51]
	v_pk_fma_f32 v[40:41], v[40:41], v[138:139], v[52:53]
	v_cndmask_b32_e64 v55, v55, v43, s[60:61]
	ds_read_b128 v[132:135], v208 offset:4352
	ds_read_b128 v[136:139], v208 offset:18432
	ds_read_b128 v[140:143], v208 offset:26624
	ds_read_b128 v[144:147], v208 offset:34816
	s_waitcnt lgkmcnt(9)
	v_pk_mul_f32 v[42:43], v[34:35], v[148:149] op_sel_hi:[0,1]
	v_pk_mul_f32 v[44:45], v[38:39], v[148:149] op_sel_hi:[0,1]
	v_pk_fma_f32 v[42:43], v[34:35], v[150:151], v[42:43] op_sel:[1,0,0]
	v_pk_fma_f32 v[44:45], v[38:39], v[150:151], v[44:45] op_sel:[1,0,0]
	v_pk_fma_f32 v[42:43], v[36:37], v[152:153], v[42:43] op_sel_hi:[0,1,1]
	v_pk_fma_f32 v[44:45], v[40:41], v[152:153], v[44:45] op_sel_hi:[0,1,1]
	v_pk_fma_f32 v[42:43], v[36:37], v[154:155], v[42:43] op_sel:[1,0,0]
	v_pk_fma_f32 v[44:45], v[40:41], v[154:155], v[44:45] op_sel:[1,0,0]
	v_pk_mul_f32 v[46:47], v[172:173], v[194:195] op_sel:[0,1]
	v_pk_mul_f32 v[48:49], v[174:175], v[194:195] op_sel:[0,1]
	v_add_f32_dpp v42, v44, v42 quad_perm:[1,0,3,2] row_mask:0xf bank_mask:0xf bound_ctrl:1
	v_add_f32_dpp v43, v45, v43 quad_perm:[1,0,3,2] row_mask:0xf bank_mask:0xf bound_ctrl:1
	v_pk_mul_f32 v[50:51], v[172:173], v[198:199] op_sel:[0,1]
	v_add_f32_dpp v42, v42, v42 quad_perm:[2,3,0,1] row_mask:0xf bank_mask:0xf bound_ctrl:1
	v_add_f32_dpp v43, v43, v43 quad_perm:[2,3,0,1] row_mask:0xf bank_mask:0xf bound_ctrl:1
	v_pk_mul_f32 v[52:53], v[174:175], v[198:199] op_sel:[0,1]
	v_add_f32_dpp v42, v42, v42 row_ror:4 row_mask:0xf bank_mask:0xf bound_ctrl:1
	v_add_f32_dpp v43, v43, v43 row_ror:4 row_mask:0xf bank_mask:0xf bound_ctrl:1
	ds_read_b128 v[148:151], v208 offset:4608
	v_add_f32_dpp v42, v42, v42 row_ror:8 row_mask:0xf bank_mask:0xf bound_ctrl:1
	v_add_f32_dpp v43, v43, v43 row_ror:8 row_mask:0xf bank_mask:0xf bound_ctrl:1
	v_pk_fma_f32 v[46:47], v[168:169], v[42:43], v[46:47] op_sel_hi:[1,0,1]
	v_mov_b32_dpp v54, v42 quad_perm:[1,0,3,2] row_mask:0xf bank_mask:0xf bound_ctrl:1
	v_pk_fma_f32 v[48:49], v[170:171], v[42:43], v[48:49] op_sel_hi:[1,0,1]
	v_fmac_f32_e32 v43, v206, v42
	v_pk_fma_f32 v[34:35], v[34:35], v[156:157], v[46:47]
	v_pk_fma_f32 v[36:37], v[36:37], v[158:159], v[48:49]
	v_pk_fma_f32 v[50:51], v[168:169], v[54:55], v[50:51] op_sel_hi:[1,0,1]
	v_pk_fma_f32 v[52:53], v[170:171], v[54:55], v[52:53] op_sel_hi:[1,0,1]
	v_fmac_f32_e32 v43, v195, v207
	v_pk_fma_f32 v[38:39], v[38:39], v[156:157], v[50:51]
	v_pk_fma_f32 v[40:41], v[40:41], v[158:159], v[52:53]
	v_cndmask_b32_e64 v55, v55, v43, s[62:63]
	ds_write_b32 v212, v55 offset:0
	ds_read_b128 v[152:155], v208 offset:4864
	ds_read_b128 v[156:159], v208 offset:18688
	ds_read_b128 v[168:171], v208 offset:26880
	ds_read_b128 v[172:175], v208 offset:35072
	s_waitcnt lgkmcnt(6)
	v_pk_mul_f32 v[42:43], v[34:35], v[128:129] op_sel_hi:[0,1]
	v_pk_mul_f32 v[44:45], v[38:39], v[128:129] op_sel_hi:[0,1]
	v_pk_fma_f32 v[42:43], v[34:35], v[130:131], v[42:43] op_sel:[1,0,0]
	v_pk_fma_f32 v[44:45], v[38:39], v[130:131], v[44:45] op_sel:[1,0,0]
	v_pk_fma_f32 v[42:43], v[36:37], v[132:133], v[42:43] op_sel_hi:[0,1,1]
	v_pk_fma_f32 v[44:45], v[40:41], v[132:133], v[44:45] op_sel_hi:[0,1,1]
	v_pk_fma_f32 v[42:43], v[36:37], v[134:135], v[42:43] op_sel:[1,0,0]
	v_pk_fma_f32 v[44:45], v[40:41], v[134:135], v[44:45] op_sel:[1,0,0]
	v_pk_mul_f32 v[46:47], v[144:145], v[176:177] op_sel_hi:[1,0]
	v_pk_mul_f32 v[48:49], v[146:147], v[176:177] op_sel_hi:[1,0]
	v_add_f32_dpp v42, v44, v42 quad_perm:[1,0,3,2] row_mask:0xf bank_mask:0xf bound_ctrl:1
	v_add_f32_dpp v43, v45, v43 quad_perm:[1,0,3,2] row_mask:0xf bank_mask:0xf bound_ctrl:1
	v_pk_mul_f32 v[50:51], v[144:145], v[180:181] op_sel_hi:[1,0]
	v_add_f32_dpp v42, v42, v42 quad_perm:[2,3,0,1] row_mask:0xf bank_mask:0xf bound_ctrl:1
	v_add_f32_dpp v43, v43, v43 quad_perm:[2,3,0,1] row_mask:0xf bank_mask:0xf bound_ctrl:1
	v_pk_mul_f32 v[52:53], v[146:147], v[180:181] op_sel_hi:[1,0]
	v_add_f32_dpp v42, v42, v42 row_ror:4 row_mask:0xf bank_mask:0xf bound_ctrl:1
	v_add_f32_dpp v43, v43, v43 row_ror:4 row_mask:0xf bank_mask:0xf bound_ctrl:1
	ds_read_b128 v[128:131], v208 offset:5120
	v_add_f32_dpp v42, v42, v42 row_ror:8 row_mask:0xf bank_mask:0xf bound_ctrl:1
	v_add_f32_dpp v43, v43, v43 row_ror:8 row_mask:0xf bank_mask:0xf bound_ctrl:1
	v_pk_fma_f32 v[46:47], v[140:141], v[42:43], v[46:47] op_sel_hi:[1,0,1]
	v_mov_b32_dpp v54, v42 quad_perm:[1,0,3,2] row_mask:0xf bank_mask:0xf bound_ctrl:1
	v_pk_fma_f32 v[48:49], v[142:143], v[42:43], v[48:49] op_sel_hi:[1,0,1]
	v_fmac_f32_e32 v43, v184, v42
	v_pk_fma_f32 v[34:35], v[34:35], v[136:137], v[46:47]
	v_pk_fma_f32 v[36:37], v[36:37], v[138:139], v[48:49]
	v_pk_fma_f32 v[50:51], v[140:141], v[54:55], v[50:51] op_sel_hi:[1,0,1]
	v_pk_fma_f32 v[52:53], v[142:143], v[54:55], v[52:53] op_sel_hi:[1,0,1]
	v_fmac_f32_e32 v43, v176, v185
	v_pk_fma_f32 v[38:39], v[38:39], v[136:137], v[50:51]
	v_pk_fma_f32 v[40:41], v[40:41], v[138:139], v[52:53]
	v_cndmask_b32_e64 v55, 0, v43, s[48:49]
	ds_read_b128 v[132:135], v208 offset:5376
	ds_read_b128 v[136:139], v208 offset:18944
	ds_read_b128 v[140:143], v208 offset:27136
	ds_read_b128 v[144:147], v208 offset:35328
	s_waitcnt lgkmcnt(5)
	v_pk_mul_f32 v[42:43], v[34:35], v[148:149] op_sel_hi:[0,1]
	v_pk_mul_f32 v[44:45], v[38:39], v[148:149] op_sel_hi:[0,1]
	v_pk_fma_f32 v[42:43], v[34:35], v[150:151], v[42:43] op_sel:[1,0,0]
	v_pk_fma_f32 v[44:45], v[38:39], v[150:151], v[44:45] op_sel:[1,0,0]
	v_pk_fma_f32 v[42:43], v[36:37], v[152:153], v[42:43] op_sel_hi:[0,1,1]
	v_pk_fma_f32 v[44:45], v[40:41], v[152:153], v[44:45] op_sel_hi:[0,1,1]
	v_pk_fma_f32 v[42:43], v[36:37], v[154:155], v[42:43] op_sel:[1,0,0]
	v_pk_fma_f32 v[44:45], v[40:41], v[154:155], v[44:45] op_sel:[1,0,0]
	v_pk_mul_f32 v[46:47], v[172:173], v[176:177] op_sel:[0,1]
	v_pk_mul_f32 v[48:49], v[174:175], v[176:177] op_sel:[0,1]
	v_add_f32_dpp v42, v44, v42 quad_perm:[1,0,3,2] row_mask:0xf bank_mask:0xf bound_ctrl:1
	v_add_f32_dpp v43, v45, v43 quad_perm:[1,0,3,2] row_mask:0xf bank_mask:0xf bound_ctrl:1
	v_pk_mul_f32 v[50:51], v[172:173], v[180:181] op_sel:[0,1]
	v_add_f32_dpp v42, v42, v42 quad_perm:[2,3,0,1] row_mask:0xf bank_mask:0xf bound_ctrl:1
	v_add_f32_dpp v43, v43, v43 quad_perm:[2,3,0,1] row_mask:0xf bank_mask:0xf bound_ctrl:1
	v_pk_mul_f32 v[52:53], v[174:175], v[180:181] op_sel:[0,1]
	v_add_f32_dpp v42, v42, v42 row_ror:4 row_mask:0xf bank_mask:0xf bound_ctrl:1
	v_add_f32_dpp v43, v43, v43 row_ror:4 row_mask:0xf bank_mask:0xf bound_ctrl:1
	ds_read_b128 v[148:151], v208 offset:5632
	v_add_f32_dpp v42, v42, v42 row_ror:8 row_mask:0xf bank_mask:0xf bound_ctrl:1
	v_add_f32_dpp v43, v43, v43 row_ror:8 row_mask:0xf bank_mask:0xf bound_ctrl:1
	v_pk_fma_f32 v[46:47], v[168:169], v[42:43], v[46:47] op_sel_hi:[1,0,1]
	v_mov_b32_dpp v54, v42 quad_perm:[1,0,3,2] row_mask:0xf bank_mask:0xf bound_ctrl:1
	v_pk_fma_f32 v[48:49], v[170:171], v[42:43], v[48:49] op_sel_hi:[1,0,1]
	v_fmac_f32_e32 v43, v186, v42
	v_pk_fma_f32 v[34:35], v[34:35], v[156:157], v[46:47]
	v_pk_fma_f32 v[36:37], v[36:37], v[158:159], v[48:49]
	v_pk_fma_f32 v[50:51], v[168:169], v[54:55], v[50:51] op_sel_hi:[1,0,1]
	v_pk_fma_f32 v[52:53], v[170:171], v[54:55], v[52:53] op_sel_hi:[1,0,1]
	v_fmac_f32_e32 v43, v177, v187
	v_pk_fma_f32 v[38:39], v[38:39], v[156:157], v[50:51]
	v_pk_fma_f32 v[40:41], v[40:41], v[158:159], v[52:53]
	v_cndmask_b32_e64 v55, v55, v43, s[50:51]
	ds_read_b128 v[152:155], v208 offset:5888
	ds_read_b128 v[156:159], v208 offset:19200
	ds_read_b128 v[168:171], v208 offset:27392
	ds_read_b128 v[172:175], v208 offset:35584
	ds_read_b128 v[192:195], v209 offset:41008
	ds_read_b128 v[196:199], v210 offset:41008
	ds_read_b128 v[200:203], v211 offset:49760
	ds_read_b128 v[204:207], v211 offset:49776
	s_waitcnt lgkmcnt(9)
	v_pk_mul_f32 v[42:43], v[34:35], v[128:129] op_sel_hi:[0,1]
	v_pk_mul_f32 v[44:45], v[38:39], v[128:129] op_sel_hi:[0,1]
	v_pk_fma_f32 v[42:43], v[34:35], v[130:131], v[42:43] op_sel:[1,0,0]
	v_pk_fma_f32 v[44:45], v[38:39], v[130:131], v[44:45] op_sel:[1,0,0]
	v_pk_fma_f32 v[42:43], v[36:37], v[132:133], v[42:43] op_sel_hi:[0,1,1]
	v_pk_fma_f32 v[44:45], v[40:41], v[132:133], v[44:45] op_sel_hi:[0,1,1]
	v_pk_fma_f32 v[42:43], v[36:37], v[134:135], v[42:43] op_sel:[1,0,0]
	v_pk_fma_f32 v[44:45], v[40:41], v[134:135], v[44:45] op_sel:[1,0,0]
	v_pk_mul_f32 v[46:47], v[144:145], v[178:179] op_sel_hi:[1,0]
	v_pk_mul_f32 v[48:49], v[146:147], v[178:179] op_sel_hi:[1,0]
	v_add_f32_dpp v42, v44, v42 quad_perm:[1,0,3,2] row_mask:0xf bank_mask:0xf bound_ctrl:1
	v_add_f32_dpp v43, v45, v43 quad_perm:[1,0,3,2] row_mask:0xf bank_mask:0xf bound_ctrl:1
	v_pk_mul_f32 v[50:51], v[144:145], v[182:183] op_sel_hi:[1,0]
	v_add_f32_dpp v42, v42, v42 quad_perm:[2,3,0,1] row_mask:0xf bank_mask:0xf bound_ctrl:1
	v_add_f32_dpp v43, v43, v43 quad_perm:[2,3,0,1] row_mask:0xf bank_mask:0xf bound_ctrl:1
	v_pk_mul_f32 v[52:53], v[146:147], v[182:183] op_sel_hi:[1,0]
	v_add_f32_dpp v42, v42, v42 row_ror:4 row_mask:0xf bank_mask:0xf bound_ctrl:1
	v_add_f32_dpp v43, v43, v43 row_ror:4 row_mask:0xf bank_mask:0xf bound_ctrl:1
	ds_read_b128 v[128:131], v208 offset:6144
	v_add_f32_dpp v42, v42, v42 row_ror:8 row_mask:0xf bank_mask:0xf bound_ctrl:1
	v_add_f32_dpp v43, v43, v43 row_ror:8 row_mask:0xf bank_mask:0xf bound_ctrl:1
	v_pk_fma_f32 v[46:47], v[140:141], v[42:43], v[46:47] op_sel_hi:[1,0,1]
	v_mov_b32_dpp v54, v42 quad_perm:[1,0,3,2] row_mask:0xf bank_mask:0xf bound_ctrl:1
	v_pk_fma_f32 v[48:49], v[142:143], v[42:43], v[48:49] op_sel_hi:[1,0,1]
	v_fmac_f32_e32 v43, v188, v42
	v_pk_fma_f32 v[34:35], v[34:35], v[136:137], v[46:47]
	v_pk_fma_f32 v[36:37], v[36:37], v[138:139], v[48:49]
	v_pk_fma_f32 v[50:51], v[140:141], v[54:55], v[50:51] op_sel_hi:[1,0,1]
	v_pk_fma_f32 v[52:53], v[142:143], v[54:55], v[52:53] op_sel_hi:[1,0,1]
	v_fmac_f32_e32 v43, v178, v189
	v_pk_fma_f32 v[38:39], v[38:39], v[136:137], v[50:51]
	v_pk_fma_f32 v[40:41], v[40:41], v[138:139], v[52:53]
	v_cndmask_b32_e64 v55, v55, v43, s[52:53]
	ds_read_b128 v[132:135], v208 offset:6400
	ds_read_b128 v[136:139], v208 offset:19456
	ds_read_b128 v[140:143], v208 offset:27648
	ds_read_b128 v[144:147], v208 offset:35840
	s_waitcnt lgkmcnt(9)
	v_pk_mul_f32 v[42:43], v[34:35], v[148:149] op_sel_hi:[0,1]
	v_pk_mul_f32 v[44:45], v[38:39], v[148:149] op_sel_hi:[0,1]
	v_pk_fma_f32 v[42:43], v[34:35], v[150:151], v[42:43] op_sel:[1,0,0]
	v_pk_fma_f32 v[44:45], v[38:39], v[150:151], v[44:45] op_sel:[1,0,0]
	v_pk_fma_f32 v[42:43], v[36:37], v[152:153], v[42:43] op_sel_hi:[0,1,1]
	v_pk_fma_f32 v[44:45], v[40:41], v[152:153], v[44:45] op_sel_hi:[0,1,1]
	v_pk_fma_f32 v[42:43], v[36:37], v[154:155], v[42:43] op_sel:[1,0,0]
	v_pk_fma_f32 v[44:45], v[40:41], v[154:155], v[44:45] op_sel:[1,0,0]
	v_pk_mul_f32 v[46:47], v[172:173], v[178:179] op_sel:[0,1]
	v_pk_mul_f32 v[48:49], v[174:175], v[178:179] op_sel:[0,1]
	v_add_f32_dpp v42, v44, v42 quad_perm:[1,0,3,2] row_mask:0xf bank_mask:0xf bound_ctrl:1
	v_add_f32_dpp v43, v45, v43 quad_perm:[1,0,3,2] row_mask:0xf bank_mask:0xf bound_ctrl:1
	v_pk_mul_f32 v[50:51], v[172:173], v[182:183] op_sel:[0,1]
	v_add_f32_dpp v42, v42, v42 quad_perm:[2,3,0,1] row_mask:0xf bank_mask:0xf bound_ctrl:1
	v_add_f32_dpp v43, v43, v43 quad_perm:[2,3,0,1] row_mask:0xf bank_mask:0xf bound_ctrl:1
	v_pk_mul_f32 v[52:53], v[174:175], v[182:183] op_sel:[0,1]
	v_add_f32_dpp v42, v42, v42 row_ror:4 row_mask:0xf bank_mask:0xf bound_ctrl:1
	v_add_f32_dpp v43, v43, v43 row_ror:4 row_mask:0xf bank_mask:0xf bound_ctrl:1
	ds_read_b128 v[148:151], v208 offset:6656
	v_add_f32_dpp v42, v42, v42 row_ror:8 row_mask:0xf bank_mask:0xf bound_ctrl:1
	v_add_f32_dpp v43, v43, v43 row_ror:8 row_mask:0xf bank_mask:0xf bound_ctrl:1
	v_pk_fma_f32 v[46:47], v[168:169], v[42:43], v[46:47] op_sel_hi:[1,0,1]
	v_mov_b32_dpp v54, v42 quad_perm:[1,0,3,2] row_mask:0xf bank_mask:0xf bound_ctrl:1
	v_pk_fma_f32 v[48:49], v[170:171], v[42:43], v[48:49] op_sel_hi:[1,0,1]
	v_fmac_f32_e32 v43, v190, v42
	v_pk_fma_f32 v[34:35], v[34:35], v[156:157], v[46:47]
	v_pk_fma_f32 v[36:37], v[36:37], v[158:159], v[48:49]
	v_pk_fma_f32 v[50:51], v[168:169], v[54:55], v[50:51] op_sel_hi:[1,0,1]
	v_pk_fma_f32 v[52:53], v[170:171], v[54:55], v[52:53] op_sel_hi:[1,0,1]
	v_fmac_f32_e32 v43, v179, v191
	v_pk_fma_f32 v[38:39], v[38:39], v[156:157], v[50:51]
	v_pk_fma_f32 v[40:41], v[40:41], v[158:159], v[52:53]
	v_cndmask_b32_e64 v55, v55, v43, s[54:55]
	ds_read_b128 v[152:155], v208 offset:6912
	ds_read_b128 v[156:159], v208 offset:19712
	ds_read_b128 v[168:171], v208 offset:27904
	ds_read_b128 v[172:175], v208 offset:36096
	s_waitcnt lgkmcnt(5)
	v_pk_mul_f32 v[42:43], v[34:35], v[128:129] op_sel_hi:[0,1]
	v_pk_mul_f32 v[44:45], v[38:39], v[128:129] op_sel_hi:[0,1]
	v_pk_fma_f32 v[42:43], v[34:35], v[130:131], v[42:43] op_sel:[1,0,0]
	v_pk_fma_f32 v[44:45], v[38:39], v[130:131], v[44:45] op_sel:[1,0,0]
	v_pk_fma_f32 v[42:43], v[36:37], v[132:133], v[42:43] op_sel_hi:[0,1,1]
	v_pk_fma_f32 v[44:45], v[40:41], v[132:133], v[44:45] op_sel_hi:[0,1,1]
	v_pk_fma_f32 v[42:43], v[36:37], v[134:135], v[42:43] op_sel:[1,0,0]
	v_pk_fma_f32 v[44:45], v[40:41], v[134:135], v[44:45] op_sel:[1,0,0]
	v_pk_mul_f32 v[46:47], v[144:145], v[192:193] op_sel_hi:[1,0]
	v_pk_mul_f32 v[48:49], v[146:147], v[192:193] op_sel_hi:[1,0]
	v_add_f32_dpp v42, v44, v42 quad_perm:[1,0,3,2] row_mask:0xf bank_mask:0xf bound_ctrl:1
	v_add_f32_dpp v43, v45, v43 quad_perm:[1,0,3,2] row_mask:0xf bank_mask:0xf bound_ctrl:1
	v_pk_mul_f32 v[50:51], v[144:145], v[196:197] op_sel_hi:[1,0]
	v_add_f32_dpp v42, v42, v42 quad_perm:[2,3,0,1] row_mask:0xf bank_mask:0xf bound_ctrl:1
	v_add_f32_dpp v43, v43, v43 quad_perm:[2,3,0,1] row_mask:0xf bank_mask:0xf bound_ctrl:1
	v_pk_mul_f32 v[52:53], v[146:147], v[196:197] op_sel_hi:[1,0]
	v_add_f32_dpp v42, v42, v42 row_ror:4 row_mask:0xf bank_mask:0xf bound_ctrl:1
	v_add_f32_dpp v43, v43, v43 row_ror:4 row_mask:0xf bank_mask:0xf bound_ctrl:1
	ds_read_b128 v[128:131], v208 offset:7168
	v_add_f32_dpp v42, v42, v42 row_ror:8 row_mask:0xf bank_mask:0xf bound_ctrl:1
	v_add_f32_dpp v43, v43, v43 row_ror:8 row_mask:0xf bank_mask:0xf bound_ctrl:1
	v_pk_fma_f32 v[46:47], v[140:141], v[42:43], v[46:47] op_sel_hi:[1,0,1]
	v_mov_b32_dpp v54, v42 quad_perm:[1,0,3,2] row_mask:0xf bank_mask:0xf bound_ctrl:1
	v_pk_fma_f32 v[48:49], v[142:143], v[42:43], v[48:49] op_sel_hi:[1,0,1]
	v_fmac_f32_e32 v43, v200, v42
	v_pk_fma_f32 v[34:35], v[34:35], v[136:137], v[46:47]
	v_pk_fma_f32 v[36:37], v[36:37], v[138:139], v[48:49]
	v_pk_fma_f32 v[50:51], v[140:141], v[54:55], v[50:51] op_sel_hi:[1,0,1]
	v_pk_fma_f32 v[52:53], v[142:143], v[54:55], v[52:53] op_sel_hi:[1,0,1]
	v_fmac_f32_e32 v43, v192, v201
	v_pk_fma_f32 v[38:39], v[38:39], v[136:137], v[50:51]
	v_pk_fma_f32 v[40:41], v[40:41], v[138:139], v[52:53]
	v_cndmask_b32_e64 v55, v55, v43, s[56:57]
	ds_read_b128 v[132:135], v208 offset:7424
	ds_read_b128 v[136:139], v208 offset:19968
	ds_read_b128 v[140:143], v208 offset:28160
	ds_read_b128 v[144:147], v208 offset:36352
	s_waitcnt lgkmcnt(5)
	v_pk_mul_f32 v[42:43], v[34:35], v[148:149] op_sel_hi:[0,1]
	v_pk_mul_f32 v[44:45], v[38:39], v[148:149] op_sel_hi:[0,1]
	v_pk_fma_f32 v[42:43], v[34:35], v[150:151], v[42:43] op_sel:[1,0,0]
	v_pk_fma_f32 v[44:45], v[38:39], v[150:151], v[44:45] op_sel:[1,0,0]
	v_pk_fma_f32 v[42:43], v[36:37], v[152:153], v[42:43] op_sel_hi:[0,1,1]
	v_pk_fma_f32 v[44:45], v[40:41], v[152:153], v[44:45] op_sel_hi:[0,1,1]
	v_pk_fma_f32 v[42:43], v[36:37], v[154:155], v[42:43] op_sel:[1,0,0]
	v_pk_fma_f32 v[44:45], v[40:41], v[154:155], v[44:45] op_sel:[1,0,0]
	v_pk_mul_f32 v[46:47], v[172:173], v[192:193] op_sel:[0,1]
	v_pk_mul_f32 v[48:49], v[174:175], v[192:193] op_sel:[0,1]
	v_add_f32_dpp v42, v44, v42 quad_perm:[1,0,3,2] row_mask:0xf bank_mask:0xf bound_ctrl:1
	v_add_f32_dpp v43, v45, v43 quad_perm:[1,0,3,2] row_mask:0xf bank_mask:0xf bound_ctrl:1
	v_pk_mul_f32 v[50:51], v[172:173], v[196:197] op_sel:[0,1]
	v_add_f32_dpp v42, v42, v42 quad_perm:[2,3,0,1] row_mask:0xf bank_mask:0xf bound_ctrl:1
	v_add_f32_dpp v43, v43, v43 quad_perm:[2,3,0,1] row_mask:0xf bank_mask:0xf bound_ctrl:1
	v_pk_mul_f32 v[52:53], v[174:175], v[196:197] op_sel:[0,1]
	v_add_f32_dpp v42, v42, v42 row_ror:4 row_mask:0xf bank_mask:0xf bound_ctrl:1
	v_add_f32_dpp v43, v43, v43 row_ror:4 row_mask:0xf bank_mask:0xf bound_ctrl:1
	ds_read_b128 v[148:151], v208 offset:7680
	v_add_f32_dpp v42, v42, v42 row_ror:8 row_mask:0xf bank_mask:0xf bound_ctrl:1
	v_add_f32_dpp v43, v43, v43 row_ror:8 row_mask:0xf bank_mask:0xf bound_ctrl:1
	v_pk_fma_f32 v[46:47], v[168:169], v[42:43], v[46:47] op_sel_hi:[1,0,1]
	v_mov_b32_dpp v54, v42 quad_perm:[1,0,3,2] row_mask:0xf bank_mask:0xf bound_ctrl:1
	v_pk_fma_f32 v[48:49], v[170:171], v[42:43], v[48:49] op_sel_hi:[1,0,1]
	v_fmac_f32_e32 v43, v202, v42
	v_pk_fma_f32 v[34:35], v[34:35], v[156:157], v[46:47]
	v_pk_fma_f32 v[36:37], v[36:37], v[158:159], v[48:49]
	v_pk_fma_f32 v[50:51], v[168:169], v[54:55], v[50:51] op_sel_hi:[1,0,1]
	v_pk_fma_f32 v[52:53], v[170:171], v[54:55], v[52:53] op_sel_hi:[1,0,1]
	v_fmac_f32_e32 v43, v193, v203
	v_pk_fma_f32 v[38:39], v[38:39], v[156:157], v[50:51]
	v_pk_fma_f32 v[40:41], v[40:41], v[158:159], v[52:53]
	v_cndmask_b32_e64 v55, v55, v43, s[58:59]
	ds_read_b128 v[152:155], v208 offset:7936
	ds_read_b128 v[156:159], v208 offset:20224
	ds_read_b128 v[168:171], v208 offset:28416
	ds_read_b128 v[172:175], v208 offset:36608
	ds_read_b128 v[176:179], v209 offset:41024
	ds_read_b128 v[180:183], v210 offset:41024
	ds_read_b128 v[184:187], v211 offset:49792
	ds_read_b128 v[188:191], v211 offset:49808
	s_waitcnt lgkmcnt(9)
	v_pk_mul_f32 v[42:43], v[34:35], v[128:129] op_sel_hi:[0,1]
	v_pk_mul_f32 v[44:45], v[38:39], v[128:129] op_sel_hi:[0,1]
	v_pk_fma_f32 v[42:43], v[34:35], v[130:131], v[42:43] op_sel:[1,0,0]
	v_pk_fma_f32 v[44:45], v[38:39], v[130:131], v[44:45] op_sel:[1,0,0]
	v_pk_fma_f32 v[42:43], v[36:37], v[132:133], v[42:43] op_sel_hi:[0,1,1]
	v_pk_fma_f32 v[44:45], v[40:41], v[132:133], v[44:45] op_sel_hi:[0,1,1]
	v_pk_fma_f32 v[42:43], v[36:37], v[134:135], v[42:43] op_sel:[1,0,0]
	v_pk_fma_f32 v[44:45], v[40:41], v[134:135], v[44:45] op_sel:[1,0,0]
	v_pk_mul_f32 v[46:47], v[144:145], v[194:195] op_sel_hi:[1,0]
	v_pk_mul_f32 v[48:49], v[146:147], v[194:195] op_sel_hi:[1,0]
	v_add_f32_dpp v42, v44, v42 quad_perm:[1,0,3,2] row_mask:0xf bank_mask:0xf bound_ctrl:1
	v_add_f32_dpp v43, v45, v43 quad_perm:[1,0,3,2] row_mask:0xf bank_mask:0xf bound_ctrl:1
	v_pk_mul_f32 v[50:51], v[144:145], v[198:199] op_sel_hi:[1,0]
	v_add_f32_dpp v42, v42, v42 quad_perm:[2,3,0,1] row_mask:0xf bank_mask:0xf bound_ctrl:1
	v_add_f32_dpp v43, v43, v43 quad_perm:[2,3,0,1] row_mask:0xf bank_mask:0xf bound_ctrl:1
	v_pk_mul_f32 v[52:53], v[146:147], v[198:199] op_sel_hi:[1,0]
	v_add_f32_dpp v42, v42, v42 row_ror:4 row_mask:0xf bank_mask:0xf bound_ctrl:1
	v_add_f32_dpp v43, v43, v43 row_ror:4 row_mask:0xf bank_mask:0xf bound_ctrl:1
	ds_read_b128 v[128:131], v208 offset:8192
	v_add_f32_dpp v42, v42, v42 row_ror:8 row_mask:0xf bank_mask:0xf bound_ctrl:1
	v_add_f32_dpp v43, v43, v43 row_ror:8 row_mask:0xf bank_mask:0xf bound_ctrl:1
	v_pk_fma_f32 v[46:47], v[140:141], v[42:43], v[46:47] op_sel_hi:[1,0,1]
	v_mov_b32_dpp v54, v42 quad_perm:[1,0,3,2] row_mask:0xf bank_mask:0xf bound_ctrl:1
	v_pk_fma_f32 v[48:49], v[142:143], v[42:43], v[48:49] op_sel_hi:[1,0,1]
	v_fmac_f32_e32 v43, v204, v42
	v_pk_fma_f32 v[34:35], v[34:35], v[136:137], v[46:47]
	v_pk_fma_f32 v[36:37], v[36:37], v[138:139], v[48:49]
	v_pk_fma_f32 v[50:51], v[140:141], v[54:55], v[50:51] op_sel_hi:[1,0,1]
	v_pk_fma_f32 v[52:53], v[142:143], v[54:55], v[52:53] op_sel_hi:[1,0,1]
	v_fmac_f32_e32 v43, v194, v205
	v_pk_fma_f32 v[38:39], v[38:39], v[136:137], v[50:51]
	v_pk_fma_f32 v[40:41], v[40:41], v[138:139], v[52:53]
	v_cndmask_b32_e64 v55, v55, v43, s[60:61]
	ds_read_b128 v[132:135], v208 offset:8448
	ds_read_b128 v[136:139], v208 offset:20480
	ds_read_b128 v[140:143], v208 offset:28672
	ds_read_b128 v[144:147], v208 offset:36864
	s_waitcnt lgkmcnt(9)
	v_pk_mul_f32 v[42:43], v[34:35], v[148:149] op_sel_hi:[0,1]
	v_pk_mul_f32 v[44:45], v[38:39], v[148:149] op_sel_hi:[0,1]
	v_pk_fma_f32 v[42:43], v[34:35], v[150:151], v[42:43] op_sel:[1,0,0]
	v_pk_fma_f32 v[44:45], v[38:39], v[150:151], v[44:45] op_sel:[1,0,0]
	v_pk_fma_f32 v[42:43], v[36:37], v[152:153], v[42:43] op_sel_hi:[0,1,1]
	v_pk_fma_f32 v[44:45], v[40:41], v[152:153], v[44:45] op_sel_hi:[0,1,1]
	v_pk_fma_f32 v[42:43], v[36:37], v[154:155], v[42:43] op_sel:[1,0,0]
	v_pk_fma_f32 v[44:45], v[40:41], v[154:155], v[44:45] op_sel:[1,0,0]
	v_pk_mul_f32 v[46:47], v[172:173], v[194:195] op_sel:[0,1]
	v_pk_mul_f32 v[48:49], v[174:175], v[194:195] op_sel:[0,1]
	v_add_f32_dpp v42, v44, v42 quad_perm:[1,0,3,2] row_mask:0xf bank_mask:0xf bound_ctrl:1
	v_add_f32_dpp v43, v45, v43 quad_perm:[1,0,3,2] row_mask:0xf bank_mask:0xf bound_ctrl:1
	v_pk_mul_f32 v[50:51], v[172:173], v[198:199] op_sel:[0,1]
	v_add_f32_dpp v42, v42, v42 quad_perm:[2,3,0,1] row_mask:0xf bank_mask:0xf bound_ctrl:1
	v_add_f32_dpp v43, v43, v43 quad_perm:[2,3,0,1] row_mask:0xf bank_mask:0xf bound_ctrl:1
	v_pk_mul_f32 v[52:53], v[174:175], v[198:199] op_sel:[0,1]
	v_add_f32_dpp v42, v42, v42 row_ror:4 row_mask:0xf bank_mask:0xf bound_ctrl:1
	v_add_f32_dpp v43, v43, v43 row_ror:4 row_mask:0xf bank_mask:0xf bound_ctrl:1
	ds_read_b128 v[148:151], v208 offset:8704
	v_add_f32_dpp v42, v42, v42 row_ror:8 row_mask:0xf bank_mask:0xf bound_ctrl:1
	v_add_f32_dpp v43, v43, v43 row_ror:8 row_mask:0xf bank_mask:0xf bound_ctrl:1
	v_pk_fma_f32 v[46:47], v[168:169], v[42:43], v[46:47] op_sel_hi:[1,0,1]
	v_mov_b32_dpp v54, v42 quad_perm:[1,0,3,2] row_mask:0xf bank_mask:0xf bound_ctrl:1
	v_pk_fma_f32 v[48:49], v[170:171], v[42:43], v[48:49] op_sel_hi:[1,0,1]
	v_fmac_f32_e32 v43, v206, v42
	v_pk_fma_f32 v[34:35], v[34:35], v[156:157], v[46:47]
	v_pk_fma_f32 v[36:37], v[36:37], v[158:159], v[48:49]
	v_pk_fma_f32 v[50:51], v[168:169], v[54:55], v[50:51] op_sel_hi:[1,0,1]
	v_pk_fma_f32 v[52:53], v[170:171], v[54:55], v[52:53] op_sel_hi:[1,0,1]
	v_fmac_f32_e32 v43, v195, v207
	v_pk_fma_f32 v[38:39], v[38:39], v[156:157], v[50:51]
	v_pk_fma_f32 v[40:41], v[40:41], v[158:159], v[52:53]
	v_cndmask_b32_e64 v55, v55, v43, s[62:63]
	ds_write_b32 v212, v55 offset:1024
	ds_read_b128 v[152:155], v208 offset:8960
	ds_read_b128 v[156:159], v208 offset:20736
	ds_read_b128 v[168:171], v208 offset:28928
	ds_read_b128 v[172:175], v208 offset:37120
	s_waitcnt lgkmcnt(6)
	v_pk_mul_f32 v[42:43], v[34:35], v[128:129] op_sel_hi:[0,1]
	v_pk_mul_f32 v[44:45], v[38:39], v[128:129] op_sel_hi:[0,1]
	v_pk_fma_f32 v[42:43], v[34:35], v[130:131], v[42:43] op_sel:[1,0,0]
	v_pk_fma_f32 v[44:45], v[38:39], v[130:131], v[44:45] op_sel:[1,0,0]
	v_pk_fma_f32 v[42:43], v[36:37], v[132:133], v[42:43] op_sel_hi:[0,1,1]
	v_pk_fma_f32 v[44:45], v[40:41], v[132:133], v[44:45] op_sel_hi:[0,1,1]
	v_pk_fma_f32 v[42:43], v[36:37], v[134:135], v[42:43] op_sel:[1,0,0]
	v_pk_fma_f32 v[44:45], v[40:41], v[134:135], v[44:45] op_sel:[1,0,0]
	v_pk_mul_f32 v[46:47], v[144:145], v[176:177] op_sel_hi:[1,0]
	v_pk_mul_f32 v[48:49], v[146:147], v[176:177] op_sel_hi:[1,0]
	v_add_f32_dpp v42, v44, v42 quad_perm:[1,0,3,2] row_mask:0xf bank_mask:0xf bound_ctrl:1
	v_add_f32_dpp v43, v45, v43 quad_perm:[1,0,3,2] row_mask:0xf bank_mask:0xf bound_ctrl:1
	v_pk_mul_f32 v[50:51], v[144:145], v[180:181] op_sel_hi:[1,0]
	v_add_f32_dpp v42, v42, v42 quad_perm:[2,3,0,1] row_mask:0xf bank_mask:0xf bound_ctrl:1
	v_add_f32_dpp v43, v43, v43 quad_perm:[2,3,0,1] row_mask:0xf bank_mask:0xf bound_ctrl:1
	v_pk_mul_f32 v[52:53], v[146:147], v[180:181] op_sel_hi:[1,0]
	v_add_f32_dpp v42, v42, v42 row_ror:4 row_mask:0xf bank_mask:0xf bound_ctrl:1
	v_add_f32_dpp v43, v43, v43 row_ror:4 row_mask:0xf bank_mask:0xf bound_ctrl:1
	ds_read_b128 v[128:131], v208 offset:9216
	v_add_f32_dpp v42, v42, v42 row_ror:8 row_mask:0xf bank_mask:0xf bound_ctrl:1
	v_add_f32_dpp v43, v43, v43 row_ror:8 row_mask:0xf bank_mask:0xf bound_ctrl:1
	v_pk_fma_f32 v[46:47], v[140:141], v[42:43], v[46:47] op_sel_hi:[1,0,1]
	v_mov_b32_dpp v54, v42 quad_perm:[1,0,3,2] row_mask:0xf bank_mask:0xf bound_ctrl:1
	v_pk_fma_f32 v[48:49], v[142:143], v[42:43], v[48:49] op_sel_hi:[1,0,1]
	v_fmac_f32_e32 v43, v184, v42
	v_pk_fma_f32 v[34:35], v[34:35], v[136:137], v[46:47]
	v_pk_fma_f32 v[36:37], v[36:37], v[138:139], v[48:49]
	v_pk_fma_f32 v[50:51], v[140:141], v[54:55], v[50:51] op_sel_hi:[1,0,1]
	v_pk_fma_f32 v[52:53], v[142:143], v[54:55], v[52:53] op_sel_hi:[1,0,1]
	v_fmac_f32_e32 v43, v176, v185
	v_pk_fma_f32 v[38:39], v[38:39], v[136:137], v[50:51]
	v_pk_fma_f32 v[40:41], v[40:41], v[138:139], v[52:53]
	v_cndmask_b32_e64 v55, 0, v43, s[48:49]
	ds_read_b128 v[132:135], v208 offset:9472
	ds_read_b128 v[136:139], v208 offset:20992
	ds_read_b128 v[140:143], v208 offset:29184
	ds_read_b128 v[144:147], v208 offset:37376
	s_waitcnt lgkmcnt(5)
	v_pk_mul_f32 v[42:43], v[34:35], v[148:149] op_sel_hi:[0,1]
	v_pk_mul_f32 v[44:45], v[38:39], v[148:149] op_sel_hi:[0,1]
	v_pk_fma_f32 v[42:43], v[34:35], v[150:151], v[42:43] op_sel:[1,0,0]
	v_pk_fma_f32 v[44:45], v[38:39], v[150:151], v[44:45] op_sel:[1,0,0]
	v_pk_fma_f32 v[42:43], v[36:37], v[152:153], v[42:43] op_sel_hi:[0,1,1]
	v_pk_fma_f32 v[44:45], v[40:41], v[152:153], v[44:45] op_sel_hi:[0,1,1]
	v_pk_fma_f32 v[42:43], v[36:37], v[154:155], v[42:43] op_sel:[1,0,0]
	v_pk_fma_f32 v[44:45], v[40:41], v[154:155], v[44:45] op_sel:[1,0,0]
	v_pk_mul_f32 v[46:47], v[172:173], v[176:177] op_sel:[0,1]
	v_pk_mul_f32 v[48:49], v[174:175], v[176:177] op_sel:[0,1]
	v_add_f32_dpp v42, v44, v42 quad_perm:[1,0,3,2] row_mask:0xf bank_mask:0xf bound_ctrl:1
	v_add_f32_dpp v43, v45, v43 quad_perm:[1,0,3,2] row_mask:0xf bank_mask:0xf bound_ctrl:1
	v_pk_mul_f32 v[50:51], v[172:173], v[180:181] op_sel:[0,1]
	v_add_f32_dpp v42, v42, v42 quad_perm:[2,3,0,1] row_mask:0xf bank_mask:0xf bound_ctrl:1
	v_add_f32_dpp v43, v43, v43 quad_perm:[2,3,0,1] row_mask:0xf bank_mask:0xf bound_ctrl:1
	v_pk_mul_f32 v[52:53], v[174:175], v[180:181] op_sel:[0,1]
	v_add_f32_dpp v42, v42, v42 row_ror:4 row_mask:0xf bank_mask:0xf bound_ctrl:1
	v_add_f32_dpp v43, v43, v43 row_ror:4 row_mask:0xf bank_mask:0xf bound_ctrl:1
	ds_read_b128 v[148:151], v208 offset:9728
	v_add_f32_dpp v42, v42, v42 row_ror:8 row_mask:0xf bank_mask:0xf bound_ctrl:1
	v_add_f32_dpp v43, v43, v43 row_ror:8 row_mask:0xf bank_mask:0xf bound_ctrl:1
	v_pk_fma_f32 v[46:47], v[168:169], v[42:43], v[46:47] op_sel_hi:[1,0,1]
	v_mov_b32_dpp v54, v42 quad_perm:[1,0,3,2] row_mask:0xf bank_mask:0xf bound_ctrl:1
	v_pk_fma_f32 v[48:49], v[170:171], v[42:43], v[48:49] op_sel_hi:[1,0,1]
	v_fmac_f32_e32 v43, v186, v42
	v_pk_fma_f32 v[34:35], v[34:35], v[156:157], v[46:47]
	v_pk_fma_f32 v[36:37], v[36:37], v[158:159], v[48:49]
	v_pk_fma_f32 v[50:51], v[168:169], v[54:55], v[50:51] op_sel_hi:[1,0,1]
	v_pk_fma_f32 v[52:53], v[170:171], v[54:55], v[52:53] op_sel_hi:[1,0,1]
	v_fmac_f32_e32 v43, v177, v187
	v_pk_fma_f32 v[38:39], v[38:39], v[156:157], v[50:51]
	v_pk_fma_f32 v[40:41], v[40:41], v[158:159], v[52:53]
	v_cndmask_b32_e64 v55, v55, v43, s[50:51]
	ds_read_b128 v[152:155], v208 offset:9984
	ds_read_b128 v[156:159], v208 offset:21248
	ds_read_b128 v[168:171], v208 offset:29440
	ds_read_b128 v[172:175], v208 offset:37632
	ds_read_b128 v[192:195], v209 offset:41040
	ds_read_b128 v[196:199], v210 offset:41040
	ds_read_b128 v[200:203], v211 offset:49824
	ds_read_b128 v[204:207], v211 offset:49840
	s_waitcnt lgkmcnt(9)
	v_pk_mul_f32 v[42:43], v[34:35], v[128:129] op_sel_hi:[0,1]
	v_pk_mul_f32 v[44:45], v[38:39], v[128:129] op_sel_hi:[0,1]
	v_pk_fma_f32 v[42:43], v[34:35], v[130:131], v[42:43] op_sel:[1,0,0]
	v_pk_fma_f32 v[44:45], v[38:39], v[130:131], v[44:45] op_sel:[1,0,0]
	v_pk_fma_f32 v[42:43], v[36:37], v[132:133], v[42:43] op_sel_hi:[0,1,1]
	v_pk_fma_f32 v[44:45], v[40:41], v[132:133], v[44:45] op_sel_hi:[0,1,1]
	v_pk_fma_f32 v[42:43], v[36:37], v[134:135], v[42:43] op_sel:[1,0,0]
	v_pk_fma_f32 v[44:45], v[40:41], v[134:135], v[44:45] op_sel:[1,0,0]
	v_pk_mul_f32 v[46:47], v[144:145], v[178:179] op_sel_hi:[1,0]
	v_pk_mul_f32 v[48:49], v[146:147], v[178:179] op_sel_hi:[1,0]
	v_add_f32_dpp v42, v44, v42 quad_perm:[1,0,3,2] row_mask:0xf bank_mask:0xf bound_ctrl:1
	v_add_f32_dpp v43, v45, v43 quad_perm:[1,0,3,2] row_mask:0xf bank_mask:0xf bound_ctrl:1
	v_pk_mul_f32 v[50:51], v[144:145], v[182:183] op_sel_hi:[1,0]
	v_add_f32_dpp v42, v42, v42 quad_perm:[2,3,0,1] row_mask:0xf bank_mask:0xf bound_ctrl:1
	v_add_f32_dpp v43, v43, v43 quad_perm:[2,3,0,1] row_mask:0xf bank_mask:0xf bound_ctrl:1
	v_pk_mul_f32 v[52:53], v[146:147], v[182:183] op_sel_hi:[1,0]
	v_add_f32_dpp v42, v42, v42 row_ror:4 row_mask:0xf bank_mask:0xf bound_ctrl:1
	v_add_f32_dpp v43, v43, v43 row_ror:4 row_mask:0xf bank_mask:0xf bound_ctrl:1
	ds_read_b128 v[128:131], v208 offset:10240
	v_add_f32_dpp v42, v42, v42 row_ror:8 row_mask:0xf bank_mask:0xf bound_ctrl:1
	v_add_f32_dpp v43, v43, v43 row_ror:8 row_mask:0xf bank_mask:0xf bound_ctrl:1
	v_pk_fma_f32 v[46:47], v[140:141], v[42:43], v[46:47] op_sel_hi:[1,0,1]
	v_mov_b32_dpp v54, v42 quad_perm:[1,0,3,2] row_mask:0xf bank_mask:0xf bound_ctrl:1
	v_pk_fma_f32 v[48:49], v[142:143], v[42:43], v[48:49] op_sel_hi:[1,0,1]
	v_fmac_f32_e32 v43, v188, v42
	v_pk_fma_f32 v[34:35], v[34:35], v[136:137], v[46:47]
	v_pk_fma_f32 v[36:37], v[36:37], v[138:139], v[48:49]
	v_pk_fma_f32 v[50:51], v[140:141], v[54:55], v[50:51] op_sel_hi:[1,0,1]
	v_pk_fma_f32 v[52:53], v[142:143], v[54:55], v[52:53] op_sel_hi:[1,0,1]
	v_fmac_f32_e32 v43, v178, v189
	v_pk_fma_f32 v[38:39], v[38:39], v[136:137], v[50:51]
	v_pk_fma_f32 v[40:41], v[40:41], v[138:139], v[52:53]
	v_cndmask_b32_e64 v55, v55, v43, s[52:53]
	ds_read_b128 v[132:135], v208 offset:10496
	ds_read_b128 v[136:139], v208 offset:21504
	ds_read_b128 v[140:143], v208 offset:29696
	ds_read_b128 v[144:147], v208 offset:37888
	s_waitcnt lgkmcnt(9)
	v_pk_mul_f32 v[42:43], v[34:35], v[148:149] op_sel_hi:[0,1]
	v_pk_mul_f32 v[44:45], v[38:39], v[148:149] op_sel_hi:[0,1]
	v_pk_fma_f32 v[42:43], v[34:35], v[150:151], v[42:43] op_sel:[1,0,0]
	v_pk_fma_f32 v[44:45], v[38:39], v[150:151], v[44:45] op_sel:[1,0,0]
	v_pk_fma_f32 v[42:43], v[36:37], v[152:153], v[42:43] op_sel_hi:[0,1,1]
	v_pk_fma_f32 v[44:45], v[40:41], v[152:153], v[44:45] op_sel_hi:[0,1,1]
	v_pk_fma_f32 v[42:43], v[36:37], v[154:155], v[42:43] op_sel:[1,0,0]
	v_pk_fma_f32 v[44:45], v[40:41], v[154:155], v[44:45] op_sel:[1,0,0]
	v_pk_mul_f32 v[46:47], v[172:173], v[178:179] op_sel:[0,1]
	v_pk_mul_f32 v[48:49], v[174:175], v[178:179] op_sel:[0,1]
	v_add_f32_dpp v42, v44, v42 quad_perm:[1,0,3,2] row_mask:0xf bank_mask:0xf bound_ctrl:1
	v_add_f32_dpp v43, v45, v43 quad_perm:[1,0,3,2] row_mask:0xf bank_mask:0xf bound_ctrl:1
	v_pk_mul_f32 v[50:51], v[172:173], v[182:183] op_sel:[0,1]
	v_add_f32_dpp v42, v42, v42 quad_perm:[2,3,0,1] row_mask:0xf bank_mask:0xf bound_ctrl:1
	v_add_f32_dpp v43, v43, v43 quad_perm:[2,3,0,1] row_mask:0xf bank_mask:0xf bound_ctrl:1
	v_pk_mul_f32 v[52:53], v[174:175], v[182:183] op_sel:[0,1]
	v_add_f32_dpp v42, v42, v42 row_ror:4 row_mask:0xf bank_mask:0xf bound_ctrl:1
	v_add_f32_dpp v43, v43, v43 row_ror:4 row_mask:0xf bank_mask:0xf bound_ctrl:1
	ds_read_b128 v[148:151], v208 offset:10752
	v_add_f32_dpp v42, v42, v42 row_ror:8 row_mask:0xf bank_mask:0xf bound_ctrl:1
	v_add_f32_dpp v43, v43, v43 row_ror:8 row_mask:0xf bank_mask:0xf bound_ctrl:1
	v_pk_fma_f32 v[46:47], v[168:169], v[42:43], v[46:47] op_sel_hi:[1,0,1]
	v_mov_b32_dpp v54, v42 quad_perm:[1,0,3,2] row_mask:0xf bank_mask:0xf bound_ctrl:1
	v_pk_fma_f32 v[48:49], v[170:171], v[42:43], v[48:49] op_sel_hi:[1,0,1]
	v_fmac_f32_e32 v43, v190, v42
	v_pk_fma_f32 v[34:35], v[34:35], v[156:157], v[46:47]
	v_pk_fma_f32 v[36:37], v[36:37], v[158:159], v[48:49]
	v_pk_fma_f32 v[50:51], v[168:169], v[54:55], v[50:51] op_sel_hi:[1,0,1]
	v_pk_fma_f32 v[52:53], v[170:171], v[54:55], v[52:53] op_sel_hi:[1,0,1]
	v_fmac_f32_e32 v43, v179, v191
	v_pk_fma_f32 v[38:39], v[38:39], v[156:157], v[50:51]
	v_pk_fma_f32 v[40:41], v[40:41], v[158:159], v[52:53]
	v_cndmask_b32_e64 v55, v55, v43, s[54:55]
	ds_read_b128 v[152:155], v208 offset:11008
	ds_read_b128 v[156:159], v208 offset:21760
	ds_read_b128 v[168:171], v208 offset:29952
	ds_read_b128 v[172:175], v208 offset:38144
	s_waitcnt lgkmcnt(5)
	v_pk_mul_f32 v[42:43], v[34:35], v[128:129] op_sel_hi:[0,1]
	v_pk_mul_f32 v[44:45], v[38:39], v[128:129] op_sel_hi:[0,1]
	v_pk_fma_f32 v[42:43], v[34:35], v[130:131], v[42:43] op_sel:[1,0,0]
	v_pk_fma_f32 v[44:45], v[38:39], v[130:131], v[44:45] op_sel:[1,0,0]
	v_pk_fma_f32 v[42:43], v[36:37], v[132:133], v[42:43] op_sel_hi:[0,1,1]
	v_pk_fma_f32 v[44:45], v[40:41], v[132:133], v[44:45] op_sel_hi:[0,1,1]
	v_pk_fma_f32 v[42:43], v[36:37], v[134:135], v[42:43] op_sel:[1,0,0]
	v_pk_fma_f32 v[44:45], v[40:41], v[134:135], v[44:45] op_sel:[1,0,0]
	v_pk_mul_f32 v[46:47], v[144:145], v[192:193] op_sel_hi:[1,0]
	v_pk_mul_f32 v[48:49], v[146:147], v[192:193] op_sel_hi:[1,0]
	v_add_f32_dpp v42, v44, v42 quad_perm:[1,0,3,2] row_mask:0xf bank_mask:0xf bound_ctrl:1
	v_add_f32_dpp v43, v45, v43 quad_perm:[1,0,3,2] row_mask:0xf bank_mask:0xf bound_ctrl:1
	v_pk_mul_f32 v[50:51], v[144:145], v[196:197] op_sel_hi:[1,0]
	v_add_f32_dpp v42, v42, v42 quad_perm:[2,3,0,1] row_mask:0xf bank_mask:0xf bound_ctrl:1
	v_add_f32_dpp v43, v43, v43 quad_perm:[2,3,0,1] row_mask:0xf bank_mask:0xf bound_ctrl:1
	v_pk_mul_f32 v[52:53], v[146:147], v[196:197] op_sel_hi:[1,0]
	v_add_f32_dpp v42, v42, v42 row_ror:4 row_mask:0xf bank_mask:0xf bound_ctrl:1
	v_add_f32_dpp v43, v43, v43 row_ror:4 row_mask:0xf bank_mask:0xf bound_ctrl:1
	ds_read_b128 v[128:131], v208 offset:11264
	v_add_f32_dpp v42, v42, v42 row_ror:8 row_mask:0xf bank_mask:0xf bound_ctrl:1
	v_add_f32_dpp v43, v43, v43 row_ror:8 row_mask:0xf bank_mask:0xf bound_ctrl:1
	v_pk_fma_f32 v[46:47], v[140:141], v[42:43], v[46:47] op_sel_hi:[1,0,1]
	v_mov_b32_dpp v54, v42 quad_perm:[1,0,3,2] row_mask:0xf bank_mask:0xf bound_ctrl:1
	v_pk_fma_f32 v[48:49], v[142:143], v[42:43], v[48:49] op_sel_hi:[1,0,1]
	v_fmac_f32_e32 v43, v200, v42
	v_pk_fma_f32 v[34:35], v[34:35], v[136:137], v[46:47]
	v_pk_fma_f32 v[36:37], v[36:37], v[138:139], v[48:49]
	v_pk_fma_f32 v[50:51], v[140:141], v[54:55], v[50:51] op_sel_hi:[1,0,1]
	v_pk_fma_f32 v[52:53], v[142:143], v[54:55], v[52:53] op_sel_hi:[1,0,1]
	v_fmac_f32_e32 v43, v192, v201
	v_pk_fma_f32 v[38:39], v[38:39], v[136:137], v[50:51]
	v_pk_fma_f32 v[40:41], v[40:41], v[138:139], v[52:53]
	v_cndmask_b32_e64 v55, v55, v43, s[56:57]
	ds_read_b128 v[132:135], v208 offset:11520
	ds_read_b128 v[136:139], v208 offset:22016
	ds_read_b128 v[140:143], v208 offset:30208
	ds_read_b128 v[144:147], v208 offset:38400
	s_waitcnt lgkmcnt(5)
	v_pk_mul_f32 v[42:43], v[34:35], v[148:149] op_sel_hi:[0,1]
	v_pk_mul_f32 v[44:45], v[38:39], v[148:149] op_sel_hi:[0,1]
	v_pk_fma_f32 v[42:43], v[34:35], v[150:151], v[42:43] op_sel:[1,0,0]
	v_pk_fma_f32 v[44:45], v[38:39], v[150:151], v[44:45] op_sel:[1,0,0]
	v_pk_fma_f32 v[42:43], v[36:37], v[152:153], v[42:43] op_sel_hi:[0,1,1]
	v_pk_fma_f32 v[44:45], v[40:41], v[152:153], v[44:45] op_sel_hi:[0,1,1]
	v_pk_fma_f32 v[42:43], v[36:37], v[154:155], v[42:43] op_sel:[1,0,0]
	v_pk_fma_f32 v[44:45], v[40:41], v[154:155], v[44:45] op_sel:[1,0,0]
	v_pk_mul_f32 v[46:47], v[172:173], v[192:193] op_sel:[0,1]
	v_pk_mul_f32 v[48:49], v[174:175], v[192:193] op_sel:[0,1]
	v_add_f32_dpp v42, v44, v42 quad_perm:[1,0,3,2] row_mask:0xf bank_mask:0xf bound_ctrl:1
	v_add_f32_dpp v43, v45, v43 quad_perm:[1,0,3,2] row_mask:0xf bank_mask:0xf bound_ctrl:1
	v_pk_mul_f32 v[50:51], v[172:173], v[196:197] op_sel:[0,1]
	v_add_f32_dpp v42, v42, v42 quad_perm:[2,3,0,1] row_mask:0xf bank_mask:0xf bound_ctrl:1
	v_add_f32_dpp v43, v43, v43 quad_perm:[2,3,0,1] row_mask:0xf bank_mask:0xf bound_ctrl:1
	v_pk_mul_f32 v[52:53], v[174:175], v[196:197] op_sel:[0,1]
	v_add_f32_dpp v42, v42, v42 row_ror:4 row_mask:0xf bank_mask:0xf bound_ctrl:1
	v_add_f32_dpp v43, v43, v43 row_ror:4 row_mask:0xf bank_mask:0xf bound_ctrl:1
	ds_read_b128 v[148:151], v208 offset:11776
	v_add_f32_dpp v42, v42, v42 row_ror:8 row_mask:0xf bank_mask:0xf bound_ctrl:1
	v_add_f32_dpp v43, v43, v43 row_ror:8 row_mask:0xf bank_mask:0xf bound_ctrl:1
	v_pk_fma_f32 v[46:47], v[168:169], v[42:43], v[46:47] op_sel_hi:[1,0,1]
	v_mov_b32_dpp v54, v42 quad_perm:[1,0,3,2] row_mask:0xf bank_mask:0xf bound_ctrl:1
	v_pk_fma_f32 v[48:49], v[170:171], v[42:43], v[48:49] op_sel_hi:[1,0,1]
	v_fmac_f32_e32 v43, v202, v42
	v_pk_fma_f32 v[34:35], v[34:35], v[156:157], v[46:47]
	v_pk_fma_f32 v[36:37], v[36:37], v[158:159], v[48:49]
	v_pk_fma_f32 v[50:51], v[168:169], v[54:55], v[50:51] op_sel_hi:[1,0,1]
	v_pk_fma_f32 v[52:53], v[170:171], v[54:55], v[52:53] op_sel_hi:[1,0,1]
	v_fmac_f32_e32 v43, v193, v203
	v_pk_fma_f32 v[38:39], v[38:39], v[156:157], v[50:51]
	v_pk_fma_f32 v[40:41], v[40:41], v[158:159], v[52:53]
	v_cndmask_b32_e64 v55, v55, v43, s[58:59]
	ds_read_b128 v[152:155], v208 offset:12032
	ds_read_b128 v[156:159], v208 offset:22272
	ds_read_b128 v[168:171], v208 offset:30464
	ds_read_b128 v[172:175], v208 offset:38656
	ds_read_b128 v[176:179], v209 offset:41056
	ds_read_b128 v[180:183], v210 offset:41056
	ds_read_b128 v[184:187], v211 offset:49856
	ds_read_b128 v[188:191], v211 offset:49872
	s_waitcnt lgkmcnt(9)
	v_pk_mul_f32 v[42:43], v[34:35], v[128:129] op_sel_hi:[0,1]
	v_pk_mul_f32 v[44:45], v[38:39], v[128:129] op_sel_hi:[0,1]
	v_pk_fma_f32 v[42:43], v[34:35], v[130:131], v[42:43] op_sel:[1,0,0]
	v_pk_fma_f32 v[44:45], v[38:39], v[130:131], v[44:45] op_sel:[1,0,0]
	v_pk_fma_f32 v[42:43], v[36:37], v[132:133], v[42:43] op_sel_hi:[0,1,1]
	v_pk_fma_f32 v[44:45], v[40:41], v[132:133], v[44:45] op_sel_hi:[0,1,1]
	v_pk_fma_f32 v[42:43], v[36:37], v[134:135], v[42:43] op_sel:[1,0,0]
	v_pk_fma_f32 v[44:45], v[40:41], v[134:135], v[44:45] op_sel:[1,0,0]
	v_pk_mul_f32 v[46:47], v[144:145], v[194:195] op_sel_hi:[1,0]
	v_pk_mul_f32 v[48:49], v[146:147], v[194:195] op_sel_hi:[1,0]
	v_add_f32_dpp v42, v44, v42 quad_perm:[1,0,3,2] row_mask:0xf bank_mask:0xf bound_ctrl:1
	v_add_f32_dpp v43, v45, v43 quad_perm:[1,0,3,2] row_mask:0xf bank_mask:0xf bound_ctrl:1
	v_pk_mul_f32 v[50:51], v[144:145], v[198:199] op_sel_hi:[1,0]
	v_add_f32_dpp v42, v42, v42 quad_perm:[2,3,0,1] row_mask:0xf bank_mask:0xf bound_ctrl:1
	v_add_f32_dpp v43, v43, v43 quad_perm:[2,3,0,1] row_mask:0xf bank_mask:0xf bound_ctrl:1
	v_pk_mul_f32 v[52:53], v[146:147], v[198:199] op_sel_hi:[1,0]
	v_add_f32_dpp v42, v42, v42 row_ror:4 row_mask:0xf bank_mask:0xf bound_ctrl:1
	v_add_f32_dpp v43, v43, v43 row_ror:4 row_mask:0xf bank_mask:0xf bound_ctrl:1
	ds_read_b128 v[128:131], v208 offset:12288
	v_add_f32_dpp v42, v42, v42 row_ror:8 row_mask:0xf bank_mask:0xf bound_ctrl:1
	v_add_f32_dpp v43, v43, v43 row_ror:8 row_mask:0xf bank_mask:0xf bound_ctrl:1
	v_pk_fma_f32 v[46:47], v[140:141], v[42:43], v[46:47] op_sel_hi:[1,0,1]
	v_mov_b32_dpp v54, v42 quad_perm:[1,0,3,2] row_mask:0xf bank_mask:0xf bound_ctrl:1
	v_pk_fma_f32 v[48:49], v[142:143], v[42:43], v[48:49] op_sel_hi:[1,0,1]
	v_fmac_f32_e32 v43, v204, v42
	v_pk_fma_f32 v[34:35], v[34:35], v[136:137], v[46:47]
	v_pk_fma_f32 v[36:37], v[36:37], v[138:139], v[48:49]
	v_pk_fma_f32 v[50:51], v[140:141], v[54:55], v[50:51] op_sel_hi:[1,0,1]
	v_pk_fma_f32 v[52:53], v[142:143], v[54:55], v[52:53] op_sel_hi:[1,0,1]
	v_fmac_f32_e32 v43, v194, v205
	v_pk_fma_f32 v[38:39], v[38:39], v[136:137], v[50:51]
	v_pk_fma_f32 v[40:41], v[40:41], v[138:139], v[52:53]
	v_cndmask_b32_e64 v55, v55, v43, s[60:61]
	ds_read_b128 v[132:135], v208 offset:12544
	ds_read_b128 v[136:139], v208 offset:22528
	ds_read_b128 v[140:143], v208 offset:30720
	ds_read_b128 v[144:147], v208 offset:38912
	s_waitcnt lgkmcnt(9)
	v_pk_mul_f32 v[42:43], v[34:35], v[148:149] op_sel_hi:[0,1]
	v_pk_mul_f32 v[44:45], v[38:39], v[148:149] op_sel_hi:[0,1]
	v_pk_fma_f32 v[42:43], v[34:35], v[150:151], v[42:43] op_sel:[1,0,0]
	v_pk_fma_f32 v[44:45], v[38:39], v[150:151], v[44:45] op_sel:[1,0,0]
	v_pk_fma_f32 v[42:43], v[36:37], v[152:153], v[42:43] op_sel_hi:[0,1,1]
	v_pk_fma_f32 v[44:45], v[40:41], v[152:153], v[44:45] op_sel_hi:[0,1,1]
	v_pk_fma_f32 v[42:43], v[36:37], v[154:155], v[42:43] op_sel:[1,0,0]
	v_pk_fma_f32 v[44:45], v[40:41], v[154:155], v[44:45] op_sel:[1,0,0]
	v_pk_mul_f32 v[46:47], v[172:173], v[194:195] op_sel:[0,1]
	v_pk_mul_f32 v[48:49], v[174:175], v[194:195] op_sel:[0,1]
	v_add_f32_dpp v42, v44, v42 quad_perm:[1,0,3,2] row_mask:0xf bank_mask:0xf bound_ctrl:1
	v_add_f32_dpp v43, v45, v43 quad_perm:[1,0,3,2] row_mask:0xf bank_mask:0xf bound_ctrl:1
	v_pk_mul_f32 v[50:51], v[172:173], v[198:199] op_sel:[0,1]
	v_add_f32_dpp v42, v42, v42 quad_perm:[2,3,0,1] row_mask:0xf bank_mask:0xf bound_ctrl:1
	v_add_f32_dpp v43, v43, v43 quad_perm:[2,3,0,1] row_mask:0xf bank_mask:0xf bound_ctrl:1
	v_pk_mul_f32 v[52:53], v[174:175], v[198:199] op_sel:[0,1]
	v_add_f32_dpp v42, v42, v42 row_ror:4 row_mask:0xf bank_mask:0xf bound_ctrl:1
	v_add_f32_dpp v43, v43, v43 row_ror:4 row_mask:0xf bank_mask:0xf bound_ctrl:1
	ds_read_b128 v[148:151], v208 offset:12800
	v_add_f32_dpp v42, v42, v42 row_ror:8 row_mask:0xf bank_mask:0xf bound_ctrl:1
	v_add_f32_dpp v43, v43, v43 row_ror:8 row_mask:0xf bank_mask:0xf bound_ctrl:1
	v_pk_fma_f32 v[46:47], v[168:169], v[42:43], v[46:47] op_sel_hi:[1,0,1]
	v_mov_b32_dpp v54, v42 quad_perm:[1,0,3,2] row_mask:0xf bank_mask:0xf bound_ctrl:1
	v_pk_fma_f32 v[48:49], v[170:171], v[42:43], v[48:49] op_sel_hi:[1,0,1]
	v_fmac_f32_e32 v43, v206, v42
	v_pk_fma_f32 v[34:35], v[34:35], v[156:157], v[46:47]
	v_pk_fma_f32 v[36:37], v[36:37], v[158:159], v[48:49]
	v_pk_fma_f32 v[50:51], v[168:169], v[54:55], v[50:51] op_sel_hi:[1,0,1]
	v_pk_fma_f32 v[52:53], v[170:171], v[54:55], v[52:53] op_sel_hi:[1,0,1]
	v_fmac_f32_e32 v43, v195, v207
	v_pk_fma_f32 v[38:39], v[38:39], v[156:157], v[50:51]
	v_pk_fma_f32 v[40:41], v[40:41], v[158:159], v[52:53]
	v_cndmask_b32_e64 v55, v55, v43, s[62:63]
	ds_write_b32 v212, v55 offset:2048
	ds_read_b128 v[152:155], v208 offset:13056
	ds_read_b128 v[156:159], v208 offset:22784
	ds_read_b128 v[168:171], v208 offset:30976
	ds_read_b128 v[172:175], v208 offset:39168
	s_waitcnt lgkmcnt(6)
	v_pk_mul_f32 v[42:43], v[34:35], v[128:129] op_sel_hi:[0,1]
	v_pk_mul_f32 v[44:45], v[38:39], v[128:129] op_sel_hi:[0,1]
	v_pk_fma_f32 v[42:43], v[34:35], v[130:131], v[42:43] op_sel:[1,0,0]
	v_pk_fma_f32 v[44:45], v[38:39], v[130:131], v[44:45] op_sel:[1,0,0]
	v_pk_fma_f32 v[42:43], v[36:37], v[132:133], v[42:43] op_sel_hi:[0,1,1]
	v_pk_fma_f32 v[44:45], v[40:41], v[132:133], v[44:45] op_sel_hi:[0,1,1]
	v_pk_fma_f32 v[42:43], v[36:37], v[134:135], v[42:43] op_sel:[1,0,0]
	v_pk_fma_f32 v[44:45], v[40:41], v[134:135], v[44:45] op_sel:[1,0,0]
	v_pk_mul_f32 v[46:47], v[144:145], v[176:177] op_sel_hi:[1,0]
	v_pk_mul_f32 v[48:49], v[146:147], v[176:177] op_sel_hi:[1,0]
	v_add_f32_dpp v42, v44, v42 quad_perm:[1,0,3,2] row_mask:0xf bank_mask:0xf bound_ctrl:1
	v_add_f32_dpp v43, v45, v43 quad_perm:[1,0,3,2] row_mask:0xf bank_mask:0xf bound_ctrl:1
	v_pk_mul_f32 v[50:51], v[144:145], v[180:181] op_sel_hi:[1,0]
	v_add_f32_dpp v42, v42, v42 quad_perm:[2,3,0,1] row_mask:0xf bank_mask:0xf bound_ctrl:1
	v_add_f32_dpp v43, v43, v43 quad_perm:[2,3,0,1] row_mask:0xf bank_mask:0xf bound_ctrl:1
	v_pk_mul_f32 v[52:53], v[146:147], v[180:181] op_sel_hi:[1,0]
	v_add_f32_dpp v42, v42, v42 row_ror:4 row_mask:0xf bank_mask:0xf bound_ctrl:1
	v_add_f32_dpp v43, v43, v43 row_ror:4 row_mask:0xf bank_mask:0xf bound_ctrl:1
	ds_read_b128 v[128:131], v208 offset:13312
	v_add_f32_dpp v42, v42, v42 row_ror:8 row_mask:0xf bank_mask:0xf bound_ctrl:1
	v_add_f32_dpp v43, v43, v43 row_ror:8 row_mask:0xf bank_mask:0xf bound_ctrl:1
	v_pk_fma_f32 v[46:47], v[140:141], v[42:43], v[46:47] op_sel_hi:[1,0,1]
	v_mov_b32_dpp v54, v42 quad_perm:[1,0,3,2] row_mask:0xf bank_mask:0xf bound_ctrl:1
	v_pk_fma_f32 v[48:49], v[142:143], v[42:43], v[48:49] op_sel_hi:[1,0,1]
	v_fmac_f32_e32 v43, v184, v42
	v_pk_fma_f32 v[34:35], v[34:35], v[136:137], v[46:47]
	v_pk_fma_f32 v[36:37], v[36:37], v[138:139], v[48:49]
	v_pk_fma_f32 v[50:51], v[140:141], v[54:55], v[50:51] op_sel_hi:[1,0,1]
	v_pk_fma_f32 v[52:53], v[142:143], v[54:55], v[52:53] op_sel_hi:[1,0,1]
	v_fmac_f32_e32 v43, v176, v185
	v_pk_fma_f32 v[38:39], v[38:39], v[136:137], v[50:51]
	v_pk_fma_f32 v[40:41], v[40:41], v[138:139], v[52:53]
	v_cndmask_b32_e64 v55, 0, v43, s[48:49]
	ds_read_b128 v[132:135], v208 offset:13568
	ds_read_b128 v[136:139], v208 offset:23040
	ds_read_b128 v[140:143], v208 offset:31232
	ds_read_b128 v[144:147], v208 offset:39424
	s_waitcnt lgkmcnt(5)
	v_pk_mul_f32 v[42:43], v[34:35], v[148:149] op_sel_hi:[0,1]
	v_pk_mul_f32 v[44:45], v[38:39], v[148:149] op_sel_hi:[0,1]
	v_pk_fma_f32 v[42:43], v[34:35], v[150:151], v[42:43] op_sel:[1,0,0]
	v_pk_fma_f32 v[44:45], v[38:39], v[150:151], v[44:45] op_sel:[1,0,0]
	v_pk_fma_f32 v[42:43], v[36:37], v[152:153], v[42:43] op_sel_hi:[0,1,1]
	v_pk_fma_f32 v[44:45], v[40:41], v[152:153], v[44:45] op_sel_hi:[0,1,1]
	v_pk_fma_f32 v[42:43], v[36:37], v[154:155], v[42:43] op_sel:[1,0,0]
	v_pk_fma_f32 v[44:45], v[40:41], v[154:155], v[44:45] op_sel:[1,0,0]
	v_pk_mul_f32 v[46:47], v[172:173], v[176:177] op_sel:[0,1]
	v_pk_mul_f32 v[48:49], v[174:175], v[176:177] op_sel:[0,1]
	v_add_f32_dpp v42, v44, v42 quad_perm:[1,0,3,2] row_mask:0xf bank_mask:0xf bound_ctrl:1
	v_add_f32_dpp v43, v45, v43 quad_perm:[1,0,3,2] row_mask:0xf bank_mask:0xf bound_ctrl:1
	v_pk_mul_f32 v[50:51], v[172:173], v[180:181] op_sel:[0,1]
	v_add_f32_dpp v42, v42, v42 quad_perm:[2,3,0,1] row_mask:0xf bank_mask:0xf bound_ctrl:1
	v_add_f32_dpp v43, v43, v43 quad_perm:[2,3,0,1] row_mask:0xf bank_mask:0xf bound_ctrl:1
	v_pk_mul_f32 v[52:53], v[174:175], v[180:181] op_sel:[0,1]
	v_add_f32_dpp v42, v42, v42 row_ror:4 row_mask:0xf bank_mask:0xf bound_ctrl:1
	v_add_f32_dpp v43, v43, v43 row_ror:4 row_mask:0xf bank_mask:0xf bound_ctrl:1
	ds_read_b128 v[148:151], v208 offset:13824
	v_add_f32_dpp v42, v42, v42 row_ror:8 row_mask:0xf bank_mask:0xf bound_ctrl:1
	v_add_f32_dpp v43, v43, v43 row_ror:8 row_mask:0xf bank_mask:0xf bound_ctrl:1
	v_pk_fma_f32 v[46:47], v[168:169], v[42:43], v[46:47] op_sel_hi:[1,0,1]
	v_mov_b32_dpp v54, v42 quad_perm:[1,0,3,2] row_mask:0xf bank_mask:0xf bound_ctrl:1
	v_pk_fma_f32 v[48:49], v[170:171], v[42:43], v[48:49] op_sel_hi:[1,0,1]
	v_fmac_f32_e32 v43, v186, v42
	v_pk_fma_f32 v[34:35], v[34:35], v[156:157], v[46:47]
	v_pk_fma_f32 v[36:37], v[36:37], v[158:159], v[48:49]
	v_pk_fma_f32 v[50:51], v[168:169], v[54:55], v[50:51] op_sel_hi:[1,0,1]
	v_pk_fma_f32 v[52:53], v[170:171], v[54:55], v[52:53] op_sel_hi:[1,0,1]
	v_fmac_f32_e32 v43, v177, v187
	v_pk_fma_f32 v[38:39], v[38:39], v[156:157], v[50:51]
	v_pk_fma_f32 v[40:41], v[40:41], v[158:159], v[52:53]
	v_cndmask_b32_e64 v55, v55, v43, s[50:51]
	ds_read_b128 v[152:155], v208 offset:14080
	ds_read_b128 v[156:159], v208 offset:23296
	ds_read_b128 v[168:171], v208 offset:31488
	ds_read_b128 v[172:175], v208 offset:39680
	ds_read_b128 v[192:195], v209 offset:41072
	ds_read_b128 v[196:199], v210 offset:41072
	ds_read_b128 v[200:203], v211 offset:49888
	ds_read_b128 v[204:207], v211 offset:49904
	s_waitcnt lgkmcnt(9)
	v_pk_mul_f32 v[42:43], v[34:35], v[128:129] op_sel_hi:[0,1]
	v_pk_mul_f32 v[44:45], v[38:39], v[128:129] op_sel_hi:[0,1]
	v_pk_fma_f32 v[42:43], v[34:35], v[130:131], v[42:43] op_sel:[1,0,0]
	v_pk_fma_f32 v[44:45], v[38:39], v[130:131], v[44:45] op_sel:[1,0,0]
	v_pk_fma_f32 v[42:43], v[36:37], v[132:133], v[42:43] op_sel_hi:[0,1,1]
	v_pk_fma_f32 v[44:45], v[40:41], v[132:133], v[44:45] op_sel_hi:[0,1,1]
	v_pk_fma_f32 v[42:43], v[36:37], v[134:135], v[42:43] op_sel:[1,0,0]
	v_pk_fma_f32 v[44:45], v[40:41], v[134:135], v[44:45] op_sel:[1,0,0]
	v_pk_mul_f32 v[46:47], v[144:145], v[178:179] op_sel_hi:[1,0]
	v_pk_mul_f32 v[48:49], v[146:147], v[178:179] op_sel_hi:[1,0]
	v_add_f32_dpp v42, v44, v42 quad_perm:[1,0,3,2] row_mask:0xf bank_mask:0xf bound_ctrl:1
	v_add_f32_dpp v43, v45, v43 quad_perm:[1,0,3,2] row_mask:0xf bank_mask:0xf bound_ctrl:1
	v_pk_mul_f32 v[50:51], v[144:145], v[182:183] op_sel_hi:[1,0]
	v_add_f32_dpp v42, v42, v42 quad_perm:[2,3,0,1] row_mask:0xf bank_mask:0xf bound_ctrl:1
	v_add_f32_dpp v43, v43, v43 quad_perm:[2,3,0,1] row_mask:0xf bank_mask:0xf bound_ctrl:1
	v_pk_mul_f32 v[52:53], v[146:147], v[182:183] op_sel_hi:[1,0]
	v_add_f32_dpp v42, v42, v42 row_ror:4 row_mask:0xf bank_mask:0xf bound_ctrl:1
	v_add_f32_dpp v43, v43, v43 row_ror:4 row_mask:0xf bank_mask:0xf bound_ctrl:1
	ds_read_b128 v[128:131], v208 offset:14336
	v_add_f32_dpp v42, v42, v42 row_ror:8 row_mask:0xf bank_mask:0xf bound_ctrl:1
	v_add_f32_dpp v43, v43, v43 row_ror:8 row_mask:0xf bank_mask:0xf bound_ctrl:1
	v_pk_fma_f32 v[46:47], v[140:141], v[42:43], v[46:47] op_sel_hi:[1,0,1]
	v_mov_b32_dpp v54, v42 quad_perm:[1,0,3,2] row_mask:0xf bank_mask:0xf bound_ctrl:1
	v_pk_fma_f32 v[48:49], v[142:143], v[42:43], v[48:49] op_sel_hi:[1,0,1]
	v_fmac_f32_e32 v43, v188, v42
	v_pk_fma_f32 v[34:35], v[34:35], v[136:137], v[46:47]
	v_pk_fma_f32 v[36:37], v[36:37], v[138:139], v[48:49]
	v_pk_fma_f32 v[50:51], v[140:141], v[54:55], v[50:51] op_sel_hi:[1,0,1]
	v_pk_fma_f32 v[52:53], v[142:143], v[54:55], v[52:53] op_sel_hi:[1,0,1]
	v_fmac_f32_e32 v43, v178, v189
	v_pk_fma_f32 v[38:39], v[38:39], v[136:137], v[50:51]
	v_pk_fma_f32 v[40:41], v[40:41], v[138:139], v[52:53]
	v_cndmask_b32_e64 v55, v55, v43, s[52:53]
	ds_read_b128 v[132:135], v208 offset:14592
	ds_read_b128 v[136:139], v208 offset:23552
	ds_read_b128 v[140:143], v208 offset:31744
	ds_read_b128 v[144:147], v208 offset:39936
	s_waitcnt lgkmcnt(9)
	v_pk_mul_f32 v[42:43], v[34:35], v[148:149] op_sel_hi:[0,1]
	v_pk_mul_f32 v[44:45], v[38:39], v[148:149] op_sel_hi:[0,1]
	v_pk_fma_f32 v[42:43], v[34:35], v[150:151], v[42:43] op_sel:[1,0,0]
	v_pk_fma_f32 v[44:45], v[38:39], v[150:151], v[44:45] op_sel:[1,0,0]
	v_pk_fma_f32 v[42:43], v[36:37], v[152:153], v[42:43] op_sel_hi:[0,1,1]
	v_pk_fma_f32 v[44:45], v[40:41], v[152:153], v[44:45] op_sel_hi:[0,1,1]
	v_pk_fma_f32 v[42:43], v[36:37], v[154:155], v[42:43] op_sel:[1,0,0]
	v_pk_fma_f32 v[44:45], v[40:41], v[154:155], v[44:45] op_sel:[1,0,0]
	v_pk_mul_f32 v[46:47], v[172:173], v[178:179] op_sel:[0,1]
	v_pk_mul_f32 v[48:49], v[174:175], v[178:179] op_sel:[0,1]
	v_add_f32_dpp v42, v44, v42 quad_perm:[1,0,3,2] row_mask:0xf bank_mask:0xf bound_ctrl:1
	v_add_f32_dpp v43, v45, v43 quad_perm:[1,0,3,2] row_mask:0xf bank_mask:0xf bound_ctrl:1
	v_pk_mul_f32 v[50:51], v[172:173], v[182:183] op_sel:[0,1]
	v_add_f32_dpp v42, v42, v42 quad_perm:[2,3,0,1] row_mask:0xf bank_mask:0xf bound_ctrl:1
	v_add_f32_dpp v43, v43, v43 quad_perm:[2,3,0,1] row_mask:0xf bank_mask:0xf bound_ctrl:1
	v_pk_mul_f32 v[52:53], v[174:175], v[182:183] op_sel:[0,1]
	v_add_f32_dpp v42, v42, v42 row_ror:4 row_mask:0xf bank_mask:0xf bound_ctrl:1
	v_add_f32_dpp v43, v43, v43 row_ror:4 row_mask:0xf bank_mask:0xf bound_ctrl:1
	ds_read_b128 v[148:151], v208 offset:14848
	v_add_f32_dpp v42, v42, v42 row_ror:8 row_mask:0xf bank_mask:0xf bound_ctrl:1
	v_add_f32_dpp v43, v43, v43 row_ror:8 row_mask:0xf bank_mask:0xf bound_ctrl:1
	v_pk_fma_f32 v[46:47], v[168:169], v[42:43], v[46:47] op_sel_hi:[1,0,1]
	v_mov_b32_dpp v54, v42 quad_perm:[1,0,3,2] row_mask:0xf bank_mask:0xf bound_ctrl:1
	v_pk_fma_f32 v[48:49], v[170:171], v[42:43], v[48:49] op_sel_hi:[1,0,1]
	v_fmac_f32_e32 v43, v190, v42
	v_pk_fma_f32 v[34:35], v[34:35], v[156:157], v[46:47]
	v_pk_fma_f32 v[36:37], v[36:37], v[158:159], v[48:49]
	v_pk_fma_f32 v[50:51], v[168:169], v[54:55], v[50:51] op_sel_hi:[1,0,1]
	v_pk_fma_f32 v[52:53], v[170:171], v[54:55], v[52:53] op_sel_hi:[1,0,1]
	v_fmac_f32_e32 v43, v179, v191
	v_pk_fma_f32 v[38:39], v[38:39], v[156:157], v[50:51]
	v_pk_fma_f32 v[40:41], v[40:41], v[158:159], v[52:53]
	v_cndmask_b32_e64 v55, v55, v43, s[54:55]
	ds_read_b128 v[152:155], v208 offset:15104
	ds_read_b128 v[156:159], v208 offset:23808
	ds_read_b128 v[168:171], v208 offset:32000
	ds_read_b128 v[172:175], v208 offset:40192
	s_waitcnt lgkmcnt(5)
	v_pk_mul_f32 v[42:43], v[34:35], v[128:129] op_sel_hi:[0,1]
	v_pk_mul_f32 v[44:45], v[38:39], v[128:129] op_sel_hi:[0,1]
	v_pk_fma_f32 v[42:43], v[34:35], v[130:131], v[42:43] op_sel:[1,0,0]
	v_pk_fma_f32 v[44:45], v[38:39], v[130:131], v[44:45] op_sel:[1,0,0]
	v_pk_fma_f32 v[42:43], v[36:37], v[132:133], v[42:43] op_sel_hi:[0,1,1]
	v_pk_fma_f32 v[44:45], v[40:41], v[132:133], v[44:45] op_sel_hi:[0,1,1]
	v_pk_fma_f32 v[42:43], v[36:37], v[134:135], v[42:43] op_sel:[1,0,0]
	v_pk_fma_f32 v[44:45], v[40:41], v[134:135], v[44:45] op_sel:[1,0,0]
	v_pk_mul_f32 v[46:47], v[144:145], v[192:193] op_sel_hi:[1,0]
	v_pk_mul_f32 v[48:49], v[146:147], v[192:193] op_sel_hi:[1,0]
	v_add_f32_dpp v42, v44, v42 quad_perm:[1,0,3,2] row_mask:0xf bank_mask:0xf bound_ctrl:1
	v_add_f32_dpp v43, v45, v43 quad_perm:[1,0,3,2] row_mask:0xf bank_mask:0xf bound_ctrl:1
	v_pk_mul_f32 v[50:51], v[144:145], v[196:197] op_sel_hi:[1,0]
	v_add_f32_dpp v42, v42, v42 quad_perm:[2,3,0,1] row_mask:0xf bank_mask:0xf bound_ctrl:1
	v_add_f32_dpp v43, v43, v43 quad_perm:[2,3,0,1] row_mask:0xf bank_mask:0xf bound_ctrl:1
	v_pk_mul_f32 v[52:53], v[146:147], v[196:197] op_sel_hi:[1,0]
	v_add_f32_dpp v42, v42, v42 row_ror:4 row_mask:0xf bank_mask:0xf bound_ctrl:1
	v_add_f32_dpp v43, v43, v43 row_ror:4 row_mask:0xf bank_mask:0xf bound_ctrl:1
	ds_read_b128 v[128:131], v208 offset:15360
	v_add_f32_dpp v42, v42, v42 row_ror:8 row_mask:0xf bank_mask:0xf bound_ctrl:1
	v_add_f32_dpp v43, v43, v43 row_ror:8 row_mask:0xf bank_mask:0xf bound_ctrl:1
	v_pk_fma_f32 v[46:47], v[140:141], v[42:43], v[46:47] op_sel_hi:[1,0,1]
	v_mov_b32_dpp v54, v42 quad_perm:[1,0,3,2] row_mask:0xf bank_mask:0xf bound_ctrl:1
	v_pk_fma_f32 v[48:49], v[142:143], v[42:43], v[48:49] op_sel_hi:[1,0,1]
	v_fmac_f32_e32 v43, v200, v42
	v_pk_fma_f32 v[34:35], v[34:35], v[136:137], v[46:47]
	v_pk_fma_f32 v[36:37], v[36:37], v[138:139], v[48:49]
	v_pk_fma_f32 v[50:51], v[140:141], v[54:55], v[50:51] op_sel_hi:[1,0,1]
	v_pk_fma_f32 v[52:53], v[142:143], v[54:55], v[52:53] op_sel_hi:[1,0,1]
	v_fmac_f32_e32 v43, v192, v201
	v_pk_fma_f32 v[38:39], v[38:39], v[136:137], v[50:51]
	v_pk_fma_f32 v[40:41], v[40:41], v[138:139], v[52:53]
	v_cndmask_b32_e64 v55, v55, v43, s[56:57]
	ds_read_b128 v[132:135], v208 offset:15616
	ds_read_b128 v[136:139], v208 offset:24064
	ds_read_b128 v[140:143], v208 offset:32256
	ds_read_b128 v[144:147], v208 offset:40448
	s_waitcnt lgkmcnt(5)
	v_pk_mul_f32 v[42:43], v[34:35], v[148:149] op_sel_hi:[0,1]
	v_pk_mul_f32 v[44:45], v[38:39], v[148:149] op_sel_hi:[0,1]
	v_pk_fma_f32 v[42:43], v[34:35], v[150:151], v[42:43] op_sel:[1,0,0]
	v_pk_fma_f32 v[44:45], v[38:39], v[150:151], v[44:45] op_sel:[1,0,0]
	v_pk_fma_f32 v[42:43], v[36:37], v[152:153], v[42:43] op_sel_hi:[0,1,1]
	v_pk_fma_f32 v[44:45], v[40:41], v[152:153], v[44:45] op_sel_hi:[0,1,1]
	v_pk_fma_f32 v[42:43], v[36:37], v[154:155], v[42:43] op_sel:[1,0,0]
	v_pk_fma_f32 v[44:45], v[40:41], v[154:155], v[44:45] op_sel:[1,0,0]
	v_pk_mul_f32 v[46:47], v[172:173], v[192:193] op_sel:[0,1]
	v_pk_mul_f32 v[48:49], v[174:175], v[192:193] op_sel:[0,1]
	v_add_f32_dpp v42, v44, v42 quad_perm:[1,0,3,2] row_mask:0xf bank_mask:0xf bound_ctrl:1
	v_add_f32_dpp v43, v45, v43 quad_perm:[1,0,3,2] row_mask:0xf bank_mask:0xf bound_ctrl:1
	v_pk_mul_f32 v[50:51], v[172:173], v[196:197] op_sel:[0,1]
	v_add_f32_dpp v42, v42, v42 quad_perm:[2,3,0,1] row_mask:0xf bank_mask:0xf bound_ctrl:1
	v_add_f32_dpp v43, v43, v43 quad_perm:[2,3,0,1] row_mask:0xf bank_mask:0xf bound_ctrl:1
	v_pk_mul_f32 v[52:53], v[174:175], v[196:197] op_sel:[0,1]
	v_add_f32_dpp v42, v42, v42 row_ror:4 row_mask:0xf bank_mask:0xf bound_ctrl:1
	v_add_f32_dpp v43, v43, v43 row_ror:4 row_mask:0xf bank_mask:0xf bound_ctrl:1
	ds_read_b128 v[148:151], v208 offset:15872
	v_add_f32_dpp v42, v42, v42 row_ror:8 row_mask:0xf bank_mask:0xf bound_ctrl:1
	v_add_f32_dpp v43, v43, v43 row_ror:8 row_mask:0xf bank_mask:0xf bound_ctrl:1
	v_pk_fma_f32 v[46:47], v[168:169], v[42:43], v[46:47] op_sel_hi:[1,0,1]
	v_mov_b32_dpp v54, v42 quad_perm:[1,0,3,2] row_mask:0xf bank_mask:0xf bound_ctrl:1
	v_pk_fma_f32 v[48:49], v[170:171], v[42:43], v[48:49] op_sel_hi:[1,0,1]
	v_fmac_f32_e32 v43, v202, v42
	v_pk_fma_f32 v[34:35], v[34:35], v[156:157], v[46:47]
	v_pk_fma_f32 v[36:37], v[36:37], v[158:159], v[48:49]
	v_pk_fma_f32 v[50:51], v[168:169], v[54:55], v[50:51] op_sel_hi:[1,0,1]
	v_pk_fma_f32 v[52:53], v[170:171], v[54:55], v[52:53] op_sel_hi:[1,0,1]
	v_fmac_f32_e32 v43, v193, v203
	v_pk_fma_f32 v[38:39], v[38:39], v[156:157], v[50:51]
	v_pk_fma_f32 v[40:41], v[40:41], v[158:159], v[52:53]
	v_cndmask_b32_e64 v55, v55, v43, s[58:59]
	ds_read_b128 v[152:155], v208 offset:16128
	ds_read_b128 v[156:159], v208 offset:24320
	ds_read_b128 v[168:171], v208 offset:32512
	ds_read_b128 v[172:175], v208 offset:40704
	s_waitcnt lgkmcnt(5)
	v_pk_mul_f32 v[42:43], v[34:35], v[128:129] op_sel_hi:[0,1]
	v_pk_mul_f32 v[44:45], v[38:39], v[128:129] op_sel_hi:[0,1]
	v_pk_fma_f32 v[42:43], v[34:35], v[130:131], v[42:43] op_sel:[1,0,0]
	v_pk_fma_f32 v[44:45], v[38:39], v[130:131], v[44:45] op_sel:[1,0,0]
	v_pk_fma_f32 v[42:43], v[36:37], v[132:133], v[42:43] op_sel_hi:[0,1,1]
	v_pk_fma_f32 v[44:45], v[40:41], v[132:133], v[44:45] op_sel_hi:[0,1,1]
	v_pk_fma_f32 v[42:43], v[36:37], v[134:135], v[42:43] op_sel:[1,0,0]
	v_pk_fma_f32 v[44:45], v[40:41], v[134:135], v[44:45] op_sel:[1,0,0]
	v_pk_mul_f32 v[46:47], v[144:145], v[194:195] op_sel_hi:[1,0]
	v_pk_mul_f32 v[48:49], v[146:147], v[194:195] op_sel_hi:[1,0]
	v_add_f32_dpp v42, v44, v42 quad_perm:[1,0,3,2] row_mask:0xf bank_mask:0xf bound_ctrl:1
	v_add_f32_dpp v43, v45, v43 quad_perm:[1,0,3,2] row_mask:0xf bank_mask:0xf bound_ctrl:1
	v_pk_mul_f32 v[50:51], v[144:145], v[198:199] op_sel_hi:[1,0]
	v_add_f32_dpp v42, v42, v42 quad_perm:[2,3,0,1] row_mask:0xf bank_mask:0xf bound_ctrl:1
	v_add_f32_dpp v43, v43, v43 quad_perm:[2,3,0,1] row_mask:0xf bank_mask:0xf bound_ctrl:1
	v_pk_mul_f32 v[52:53], v[146:147], v[198:199] op_sel_hi:[1,0]
	v_add_f32_dpp v42, v42, v42 row_ror:4 row_mask:0xf bank_mask:0xf bound_ctrl:1
	v_add_f32_dpp v43, v43, v43 row_ror:4 row_mask:0xf bank_mask:0xf bound_ctrl:1
	s_nop 0
	v_add_f32_dpp v42, v42, v42 row_ror:8 row_mask:0xf bank_mask:0xf bound_ctrl:1
	v_add_f32_dpp v43, v43, v43 row_ror:8 row_mask:0xf bank_mask:0xf bound_ctrl:1
	v_pk_fma_f32 v[46:47], v[140:141], v[42:43], v[46:47] op_sel_hi:[1,0,1]
	v_mov_b32_dpp v54, v42 quad_perm:[1,0,3,2] row_mask:0xf bank_mask:0xf bound_ctrl:1
	v_pk_fma_f32 v[48:49], v[142:143], v[42:43], v[48:49] op_sel_hi:[1,0,1]
	v_fmac_f32_e32 v43, v204, v42
	v_pk_fma_f32 v[34:35], v[34:35], v[136:137], v[46:47]
	v_pk_fma_f32 v[36:37], v[36:37], v[138:139], v[48:49]
	v_pk_fma_f32 v[50:51], v[140:141], v[54:55], v[50:51] op_sel_hi:[1,0,1]
	v_pk_fma_f32 v[52:53], v[142:143], v[54:55], v[52:53] op_sel_hi:[1,0,1]
	v_fmac_f32_e32 v43, v194, v205
	v_pk_fma_f32 v[38:39], v[38:39], v[136:137], v[50:51]
	v_pk_fma_f32 v[40:41], v[40:41], v[138:139], v[52:53]
	v_cndmask_b32_e64 v55, v55, v43, s[60:61]
	s_waitcnt lgkmcnt(0)
	v_pk_mul_f32 v[42:43], v[34:35], v[148:149] op_sel_hi:[0,1]
	v_pk_mul_f32 v[44:45], v[38:39], v[148:149] op_sel_hi:[0,1]
	v_pk_fma_f32 v[42:43], v[34:35], v[150:151], v[42:43] op_sel:[1,0,0]
	v_pk_fma_f32 v[44:45], v[38:39], v[150:151], v[44:45] op_sel:[1,0,0]
	v_pk_fma_f32 v[42:43], v[36:37], v[152:153], v[42:43] op_sel_hi:[0,1,1]
	v_pk_fma_f32 v[44:45], v[40:41], v[152:153], v[44:45] op_sel_hi:[0,1,1]
	v_pk_fma_f32 v[42:43], v[36:37], v[154:155], v[42:43] op_sel:[1,0,0]
	v_pk_fma_f32 v[44:45], v[40:41], v[154:155], v[44:45] op_sel:[1,0,0]
	v_pk_mul_f32 v[46:47], v[172:173], v[194:195] op_sel:[0,1]
	v_pk_mul_f32 v[48:49], v[174:175], v[194:195] op_sel:[0,1]
	v_add_f32_dpp v42, v44, v42 quad_perm:[1,0,3,2] row_mask:0xf bank_mask:0xf bound_ctrl:1
	v_add_f32_dpp v43, v45, v43 quad_perm:[1,0,3,2] row_mask:0xf bank_mask:0xf bound_ctrl:1
	v_pk_mul_f32 v[50:51], v[172:173], v[198:199] op_sel:[0,1]
	v_add_f32_dpp v42, v42, v42 quad_perm:[2,3,0,1] row_mask:0xf bank_mask:0xf bound_ctrl:1
	v_add_f32_dpp v43, v43, v43 quad_perm:[2,3,0,1] row_mask:0xf bank_mask:0xf bound_ctrl:1
	v_pk_mul_f32 v[52:53], v[174:175], v[198:199] op_sel:[0,1]
	v_add_f32_dpp v42, v42, v42 row_ror:4 row_mask:0xf bank_mask:0xf bound_ctrl:1
	v_add_f32_dpp v43, v43, v43 row_ror:4 row_mask:0xf bank_mask:0xf bound_ctrl:1
	s_nop 0
	v_add_f32_dpp v42, v42, v42 row_ror:8 row_mask:0xf bank_mask:0xf bound_ctrl:1
	v_add_f32_dpp v43, v43, v43 row_ror:8 row_mask:0xf bank_mask:0xf bound_ctrl:1
	v_pk_fma_f32 v[46:47], v[168:169], v[42:43], v[46:47] op_sel_hi:[1,0,1]
	v_mov_b32_dpp v54, v42 quad_perm:[1,0,3,2] row_mask:0xf bank_mask:0xf bound_ctrl:1
	v_pk_fma_f32 v[48:49], v[170:171], v[42:43], v[48:49] op_sel_hi:[1,0,1]
	v_fmac_f32_e32 v43, v206, v42
	v_pk_fma_f32 v[34:35], v[34:35], v[156:157], v[46:47]
	v_pk_fma_f32 v[36:37], v[36:37], v[158:159], v[48:49]
	v_pk_fma_f32 v[50:51], v[168:169], v[54:55], v[50:51] op_sel_hi:[1,0,1]
	v_pk_fma_f32 v[52:53], v[170:171], v[54:55], v[52:53] op_sel_hi:[1,0,1]
	v_fmac_f32_e32 v43, v195, v207
	v_pk_fma_f32 v[38:39], v[38:39], v[156:157], v[50:51]
	v_pk_fma_f32 v[40:41], v[40:41], v[158:159], v[52:53]
	v_cndmask_b32_e64 v55, v55, v43, s[62:63]
	ds_write_b32 v212, v55 offset:3072
	s_setprio 0

.LBB0_834:
	s_or_b64 exec, exec, s[8:9]
	s_waitcnt lgkmcnt(0)
	s_and_saveexec_b64 s[8:9], s[42:43]
	s_xor_b64 s[18:19], exec, s[8:9]
	s_cbranch_execz .LBB0_836

.LBB0_836:
	s_andn2_saveexec_b64 s[8:9], s[18:19]
	s_cbranch_execz .LBB0_807
	s_cmp_eq_u32 s20, 0x7f0000
	s_cbranch_scc1 .LBB0_807
	s_add_u32 s100, s100, 4
	v_mov_b32_e32 v42, 0x21f00
	v_mov_b32_e32 v43, 1
	s_mov_b64 s[18:19], exec
	s_mov_b64 exec, 1
	ds_add_u32 v42, v43
	s_mov_b64 exec, s[18:19]
	s_mov_b32 s101, 0x1000
.Lscan_mid_spin:
	ds_read_b32 v43, v42
	s_waitcnt lgkmcnt(0)
	v_readfirstlane_b32 s18, v43
	s_cmp_ge_u32 s18, s100
	s_cbranch_scc1 .Lscan_mid_go
	s_sleep 1
	s_sub_u32 s101, s101, 1
	s_cmp_lg_u32 s101, 0
	s_cbranch_scc1 .Lscan_mid_spin
.Lscan_mid_go:
	v_lshl_add_u32 v54, v97, 2, s4
	ds_read_b128 v[46:49], v54 offset:16384
	ds_read_b128 v[42:45], v54 offset:24576
	s_waitcnt vmcnt(7)
	v_lshlrev_b32_e32 v50, 16, v76
	v_and_b32_e32 v51, 0xffff0000, v76
	v_lshlrev_b32_e32 v52, 16, v77
	s_and_b64 vcc, exec, s[46:47]
	v_and_b32_e32 v53, 0xffff0000, v77
	s_cbranch_vccnz .LBB0_840
	v_lshlrev_b32_e32 v122, 16, v75
	v_and_b32_e32 v123, 0xffff0000, v75
	v_sub_f32_e32 v127, v123, v53
	v_sub_f32_e32 v126, v122, v52
	ds_read_b128 v[122:125], v54 offset:32768
	v_lshlrev_b32_e32 v55, 16, v74
	v_and_b32_e32 v56, 0xffff0000, v74
	v_sub_f32_e32 v57, v56, v51
	v_sub_f32_e32 v56, v55, v50
	s_waitcnt lgkmcnt(0)
	v_pk_fma_f32 v[52:53], v[126:127], v[124:125], v[52:53]
	v_pk_fma_f32 v[50:51], v[56:57], v[122:123], v[50:51]

.LBB0_1498:
	v_readlane_b32 s0, v253, 59
	v_readlane_b32 s1, v253, 60
	s_xor_b64 s[4:5], s[0:1], -1
	s_mov_b64 s[0:1], 0
	s_and_b64 vcc, exec, s[4:5]
	s_cbranch_vccz .LBB0_1552
	s_waitcnt vmcnt(0)
	s_waitcnt vmcnt(0) lgkmcnt(0)
	s_barrier
	s_mov_b64 s[0:1], exec
	v_readlane_b32 s4, v252, 5
	v_readlane_b32 s5, v252, 6
	s_and_b64 s[4:5], s[0:1], s[4:5]
	s_mov_b64 exec, s[4:5]
	s_cbranch_execz .LBB0_1551
	v_readlane_b32 s4, v253, 27
	s_waitcnt vmcnt(0) expcnt(0) lgkmcnt(0)
	s_nop 0
	v_mov_b32_e32 v0, s4
	ds_read_b32 v3, v0
	v_readlane_b32 s4, v253, 28
	s_waitcnt lgkmcnt(0)
	v_cmp_ne_u32_e32 vcc, 0, v3
	v_mov_b32_e32 v0, s4
	ds_read_b32 v2, v0
	s_cbranch_vccnz .LBB0_1515
	s_mov_b32 s4, 1
	s_branch .LBB0_1503

	.amdhsa_kernel _Z9yoco_mega6Params
		.amdhsa_group_segment_fixed_size 0
		.amdhsa_private_segment_fixed_size 0
		.amdhsa_kernarg_size 512
		.amdhsa_user_sgpr_count 2
		.amdhsa_user_sgpr_dispatch_ptr 0
		.amdhsa_user_sgpr_queue_ptr 0
		.amdhsa_user_sgpr_kernarg_segment_ptr 1
		.amdhsa_user_sgpr_dispatch_id 0
		.amdhsa_user_sgpr_kernarg_preload_length 0
		.amdhsa_user_sgpr_kernarg_preload_offset 0
		.amdhsa_user_sgpr_private_segment_size 0
		.amdhsa_uses_dynamic_stack 0
		.amdhsa_enable_private_segment 0
		.amdhsa_system_sgpr_workgroup_id_x 1
		.amdhsa_system_sgpr_workgroup_id_y 0
		.amdhsa_system_sgpr_workgroup_id_z 0
		.amdhsa_system_sgpr_workgroup_info 0
		.amdhsa_system_vgpr_workitem_id 2
		.amdhsa_next_free_vgpr 256
		.amdhsa_next_free_sgpr 102
		.amdhsa_accum_offset 256
		.amdhsa_reserve_vcc 1
		.amdhsa_float_round_mode_32 0
		.amdhsa_float_round_mode_16_64 0
		.amdhsa_float_denorm_mode_32 3
		.amdhsa_float_denorm_mode_16_64 3
		.amdhsa_dx10_clamp 1
		.amdhsa_ieee_mode 1
		.amdhsa_fp16_overflow 0
		.amdhsa_tg_split 0
		.amdhsa_exception_fp_ieee_invalid_op 0
		.amdhsa_exception_fp_denorm_src 0
		.amdhsa_exception_fp_ieee_div_zero 0
		.amdhsa_exception_fp_ieee_overflow 0
		.amdhsa_exception_fp_ieee_underflow 0
		.amdhsa_exception_fp_ieee_inexact 0
		.amdhsa_exception_int_div_zero 0
	.end_amdhsa_kernel

amdhsa.kernels:
  - .agpr_count:     0
    .args:
      - .offset:         0
        .size:           256
        .value_kind:     by_value
      - .offset:         256
        .size:           4
        .value_kind:     hidden_block_count_x
      - .offset:         260
        .size:           4
        .value_kind:     hidden_block_count_y
      - .offset:         264
        .size:           4
        .value_kind:     hidden_block_count_z
      - .offset:         268
        .size:           2
        .value_kind:     hidden_group_size_x
      - .offset:         270
        .size:           2
        .value_kind:     hidden_group_size_y
      - .offset:         272
        .size:           2
        .value_kind:     hidden_group_size_z
      - .offset:         274
        .size:           2
        .value_kind:     hidden_remainder_x
      - .offset:         276
        .size:           2
        .value_kind:     hidden_remainder_y
      - .offset:         278
        .size:           2
        .value_kind:     hidden_remainder_z
      - .offset:         296
        .size:           8
        .value_kind:     hidden_global_offset_x
      - .offset:         304
        .size:           8
        .value_kind:     hidden_global_offset_y
      - .offset:         312
        .size:           8
        .value_kind:     hidden_global_offset_z
      - .offset:         320
        .size:           2
        .value_kind:     hidden_grid_dims
      - .offset:         344
        .size:           8
        .value_kind:     hidden_multigrid_sync_arg
      - .offset:         376
        .size:           4
        .value_kind:     hidden_dynamic_lds_size
    .group_segment_fixed_size: 0
    .kernarg_segment_align: 8
    .kernarg_segment_size: 512
    .language:       OpenCL C
    .language_version:
      - 2
      - 0
    .max_flat_workgroup_size: 512
    .name:           _Z9yoco_mega6Params
    .private_segment_fixed_size: 0
    .sgpr_count:     108
    .sgpr_spill_count: 626
    .symbol:         _Z9yoco_mega6Params.kd
    .uniform_work_group_size: 1
    .uses_dynamic_stack: false
    .vgpr_count:     256
    .vgpr_spill_count: 0
    .wavefront_size: 64
